# prompt scan asm blocks regenerated: fused pa chain, o-partial as fma chain, vk muls as DPP fillers, lgkm wait moved to end of step
# speedup vs baseline: 1.0077x; 1.0077x over previous
; #define WSB_DECL unsigned char* wsb = A.ws; asm volatile("" : "+s"(wsb))
; __global__ void __launch_bounds__(NWAVES * 64, 2) hybrid_fwd(Args A) {
;     ...
;     for (int ph = lo; ph < hi; ++ph) {
;       const int l = (ph - 1) / 6, s = (ph == 0) ? -1 : (ph - 1) % 6;
;       WSB_DECL;
;       const int reps = ((ph > 0 && ((DUP_MASK >> s) & 1) && !(s == 5 && l == DEPTH - 1)) || (ph == 0 && (DUP_MASK & 64))) ? 2 : 1;
.LBB0_19:
	s_mov_b64 s[0:1], s[24:25]
	v_writelane_b32 v255, s0, 36
	s_nop 1
	v_writelane_b32 v255, s1, 37
	v_writelane_b32 v255, s2, 38
	v_writelane_b32 v255, s3, 39
	v_sub_co_u32_e64 v0, s[0:1], s24, 1
	s_nop 0
	v_readfirstlane_b32 s2, v0
	s_mul_hi_i32 s3, s2, 0x2aaaaaab
	s_lshr_b32 s8, s3, 31
	s_add_i32 s8, s3, s8
	s_mul_i32 s3, s8, 6
	s_sub_i32 s10, s2, s3
	s_cmp_eq_u32 s10, 5
	s_cselect_b64 s[2:3], -1, 0
	v_writelane_b32 v255, s2, 40
	s_andn2_b64 vcc, exec, s[0:1]
	s_mov_b64 s[0:1], -1
	v_writelane_b32 v255, s3, 41
	v_readlane_b32 s2, v253, 4
	v_readlane_b32 s3, v253, 5
	s_cbranch_vccnz .LBB0_20
	s_getpc_b64 s[98:99]

.LBB0_685:
	ds_read_b128 v[164:167], v5 offset:0
	ds_read_b128 v[168:171], v5 offset:256
	ds_read_b128 v[172:175], v5 offset:512
	ds_read_b128 v[176:179], v5 offset:768
	ds_read_b128 v[180:183], v5 offset:1024
	ds_read_b32 v184, v9 offset:0
	ds_read_b128 v[186:189], v5 offset:1536
	ds_read_b128 v[190:193], v5 offset:1792
	ds_read_b128 v[194:197], v5 offset:2048
	ds_read_b128 v[198:201], v5 offset:2304
	ds_read_b128 v[202:205], v5 offset:2560
	ds_read_b32 v206, v9 offset:1536
	s_waitcnt lgkmcnt(0)
	v_mul_f32 v137, v184, v176
	v_mul_f32 v138, v184, v177
	v_mul_f32 v145, v2, v164
	v_fma_f32 v145, v13, v165, v145
	v_fma_f32 v145, v12, v166, v145
	v_fma_f32 v145, v8, v167, v145
	ds_read_b128 v[208:211], v5 offset:3072
	ds_read_b128 v[212:215], v5 offset:3328
	ds_read_b128 v[216:219], v5 offset:3584
	ds_read_b128 v[220:223], v5 offset:3840
	ds_read_b128 v[224:227], v5 offset:4096
	ds_read_b32 v228, v9 offset:3072
	v_add_f32_dpp v145, v145, v145 quad_perm:[1,0,3,2] row_mask:0xf bank_mask:0xf bound_ctrl:1
	s_nop 0
	s_nop 0
	v_add_f32_dpp v145, v145, v145 quad_perm:[2,3,0,1] row_mask:0xf bank_mask:0xf bound_ctrl:1
	s_nop 0
	s_nop 0
	v_add_f32_dpp v145, v145, v145 row_half_mirror row_mask:0xf bank_mask:0xf bound_ctrl:1
	v_mul_f32 v139, v184, v178
	v_mul_f32 v140, v184, v179
	v_add_f32_dpp v145, v145, v145 row_mirror row_mask:0xf bank_mask:0xf bound_ctrl:1
	v_fma_f32 v137, -v145, v168, v137
	v_fma_f32 v138, -v145, v169, v138
	v_fma_f32 v139, -v145, v170, v139
	v_fma_f32 v140, -v145, v171, v140
	v_fma_f32 v2, v2, v172, v137
	v_fma_f32 v13, v13, v173, v138
	v_fma_f32 v12, v12, v174, v139
	v_fma_f32 v8, v8, v175, v140
	s_waitcnt lgkmcnt(6)
	v_mul_f32 v137, v206, v198
	v_mul_f32 v138, v206, v199
	v_mul_f32 v145, v2, v186
	v_fma_f32 v145, v13, v187, v145
	v_fma_f32 v145, v12, v188, v145
	v_fma_f32 v145, v8, v189, v145
	ds_read_b128 v[230:233], v5 offset:4608
	ds_read_b128 v[234:237], v5 offset:4864
	ds_read_b128 v[238:241], v5 offset:5120
	ds_read_b128 v[242:245], v5 offset:5376
	ds_read_b128 v[246:249], v5 offset:5632
	ds_read_b32 v250, v9 offset:4608
	v_add_f32_dpp v145, v145, v145 quad_perm:[1,0,3,2] row_mask:0xf bank_mask:0xf bound_ctrl:1
	v_mul_f32 v148, v2, v180
	v_fma_f32 v148, v13, v181, v148
	v_add_f32_dpp v145, v145, v145 quad_perm:[2,3,0,1] row_mask:0xf bank_mask:0xf bound_ctrl:1
	v_fma_f32 v148, v12, v182, v148
	v_fma_f32 v148, v8, v183, v148
	v_add_f32_dpp v145, v145, v145 row_half_mirror row_mask:0xf bank_mask:0xf bound_ctrl:1
	v_mul_f32 v139, v206, v200
	v_mul_f32 v140, v206, v201
	v_add_f32_dpp v145, v145, v145 row_mirror row_mask:0xf bank_mask:0xf bound_ctrl:1
	v_fma_f32 v137, -v145, v190, v137
	v_fma_f32 v138, -v145, v191, v138
	v_fma_f32 v139, -v145, v192, v139
	v_fma_f32 v140, -v145, v193, v140
	v_fma_f32 v2, v2, v194, v137
	v_fma_f32 v13, v13, v195, v138
	v_fma_f32 v12, v12, v196, v139
	v_fma_f32 v8, v8, v197, v140
	s_waitcnt lgkmcnt(6)
	v_mul_f32 v137, v228, v220
	v_mul_f32 v138, v228, v221
	v_mul_f32 v145, v2, v208
	v_fma_f32 v145, v13, v209, v145
	v_fma_f32 v145, v12, v210, v145
	v_fma_f32 v145, v8, v211, v145
	ds_read_b128 v[164:167], v5 offset:6144
	ds_read_b128 v[168:171], v5 offset:6400
	ds_read_b128 v[172:175], v5 offset:6656
	ds_read_b128 v[176:179], v5 offset:6912
	ds_read_b128 v[180:183], v5 offset:7168
	ds_read_b32 v184, v9 offset:6144
	v_add_f32_dpp v145, v145, v145 quad_perm:[1,0,3,2] row_mask:0xf bank_mask:0xf bound_ctrl:1
	v_mul_f32 v149, v2, v202
	v_fma_f32 v149, v13, v203, v149
	v_add_f32_dpp v145, v145, v145 quad_perm:[2,3,0,1] row_mask:0xf bank_mask:0xf bound_ctrl:1
	v_fma_f32 v149, v12, v204, v149
	v_fma_f32 v149, v8, v205, v149
	v_add_f32_dpp v145, v145, v145 row_half_mirror row_mask:0xf bank_mask:0xf bound_ctrl:1
	v_mul_f32 v139, v228, v222
	v_mul_f32 v140, v228, v223
	v_add_f32_dpp v145, v145, v145 row_mirror row_mask:0xf bank_mask:0xf bound_ctrl:1
	v_fma_f32 v137, -v145, v212, v137
	v_fma_f32 v138, -v145, v213, v138
	v_fma_f32 v139, -v145, v214, v139
	v_fma_f32 v140, -v145, v215, v140
	v_fma_f32 v2, v2, v216, v137
	v_fma_f32 v13, v13, v217, v138
	v_fma_f32 v12, v12, v218, v139
	v_fma_f32 v8, v8, v219, v140
	s_waitcnt lgkmcnt(6)
	v_mul_f32 v137, v250, v242
	v_mul_f32 v138, v250, v243
	v_mul_f32 v145, v2, v230
	v_fma_f32 v145, v13, v231, v145
	v_fma_f32 v145, v12, v232, v145
	v_fma_f32 v145, v8, v233, v145
	ds_read_b128 v[186:189], v5 offset:7680
	ds_read_b128 v[190:193], v5 offset:7936
	ds_read_b128 v[194:197], v5 offset:8192
	ds_read_b128 v[198:201], v5 offset:8448
	ds_read_b128 v[202:205], v5 offset:8704
	ds_read_b32 v206, v9 offset:7680
	v_add_f32_dpp v145, v145, v145 quad_perm:[1,0,3,2] row_mask:0xf bank_mask:0xf bound_ctrl:1
	v_mul_f32 v150, v2, v224
	v_fma_f32 v150, v13, v225, v150
	v_add_f32_dpp v145, v145, v145 quad_perm:[2,3,0,1] row_mask:0xf bank_mask:0xf bound_ctrl:1
	v_fma_f32 v150, v12, v226, v150
	v_fma_f32 v150, v8, v227, v150
	v_add_f32_dpp v145, v145, v145 row_half_mirror row_mask:0xf bank_mask:0xf bound_ctrl:1
	v_mul_f32 v139, v250, v244
	v_mul_f32 v140, v250, v245
	v_add_f32_dpp v145, v145, v145 row_mirror row_mask:0xf bank_mask:0xf bound_ctrl:1
	v_fma_f32 v137, -v145, v234, v137
	v_fma_f32 v138, -v145, v235, v138
	v_fma_f32 v139, -v145, v236, v139
	v_fma_f32 v140, -v145, v237, v140
	v_fma_f32 v2, v2, v238, v137
	v_fma_f32 v13, v13, v239, v138
	v_fma_f32 v12, v12, v240, v139
	v_fma_f32 v8, v8, v241, v140
	s_waitcnt lgkmcnt(6)
	v_mul_f32 v137, v184, v176
	v_mul_f32 v138, v184, v177
	v_mul_f32 v145, v2, v164
	v_fma_f32 v145, v13, v165, v145
	v_fma_f32 v145, v12, v166, v145
	v_fma_f32 v145, v8, v167, v145
	ds_read_b128 v[208:211], v5 offset:9216
	ds_read_b128 v[212:215], v5 offset:9472
	ds_read_b128 v[216:219], v5 offset:9728
	ds_read_b128 v[220:223], v5 offset:9984
	ds_read_b128 v[224:227], v5 offset:10240
	ds_read_b32 v228, v9 offset:9216
	v_add_f32_dpp v145, v145, v145 quad_perm:[1,0,3,2] row_mask:0xf bank_mask:0xf bound_ctrl:1
	v_mul_f32 v151, v2, v246
	v_fma_f32 v151, v13, v247, v151
	v_add_f32_dpp v145, v145, v145 quad_perm:[2,3,0,1] row_mask:0xf bank_mask:0xf bound_ctrl:1
	v_fma_f32 v151, v12, v248, v151
	v_fma_f32 v151, v8, v249, v151
	v_add_f32_dpp v145, v145, v145 row_half_mirror row_mask:0xf bank_mask:0xf bound_ctrl:1
	v_mul_f32 v139, v184, v178
	v_mul_f32 v140, v184, v179
	v_add_f32_dpp v145, v145, v145 row_mirror row_mask:0xf bank_mask:0xf bound_ctrl:1
	v_fma_f32 v137, -v145, v168, v137
	v_fma_f32 v138, -v145, v169, v138
	v_fma_f32 v139, -v145, v170, v139
	v_fma_f32 v140, -v145, v171, v140
	v_fma_f32 v2, v2, v172, v137
	v_fma_f32 v13, v13, v173, v138
	v_fma_f32 v12, v12, v174, v139
	v_fma_f32 v8, v8, v175, v140
	s_waitcnt lgkmcnt(6)
	v_mul_f32 v137, v206, v198
	v_mul_f32 v138, v206, v199
	v_mul_f32 v145, v2, v186
	v_fma_f32 v145, v13, v187, v145
	v_fma_f32 v145, v12, v188, v145
	v_fma_f32 v145, v8, v189, v145
	ds_read_b128 v[230:233], v5 offset:10752
	ds_read_b128 v[234:237], v5 offset:11008
	ds_read_b128 v[238:241], v5 offset:11264
	ds_read_b128 v[242:245], v5 offset:11520
	ds_read_b128 v[246:249], v5 offset:11776
	ds_read_b32 v250, v9 offset:10752
	v_add_f32_dpp v145, v145, v145 quad_perm:[1,0,3,2] row_mask:0xf bank_mask:0xf bound_ctrl:1
	v_mul_f32 v152, v2, v180
	v_fma_f32 v152, v13, v181, v152
	v_add_f32_dpp v145, v145, v145 quad_perm:[2,3,0,1] row_mask:0xf bank_mask:0xf bound_ctrl:1
	v_fma_f32 v152, v12, v182, v152
	v_fma_f32 v152, v8, v183, v152
	v_add_f32_dpp v145, v145, v145 row_half_mirror row_mask:0xf bank_mask:0xf bound_ctrl:1
	v_mul_f32 v139, v206, v200
	v_mul_f32 v140, v206, v201
	v_add_f32_dpp v145, v145, v145 row_mirror row_mask:0xf bank_mask:0xf bound_ctrl:1
	v_fma_f32 v137, -v145, v190, v137
	v_fma_f32 v138, -v145, v191, v138
	v_fma_f32 v139, -v145, v192, v139
	v_fma_f32 v140, -v145, v193, v140
	v_fma_f32 v2, v2, v194, v137
	v_fma_f32 v13, v13, v195, v138
	v_fma_f32 v12, v12, v196, v139
	v_fma_f32 v8, v8, v197, v140
	s_waitcnt lgkmcnt(6)
	v_mul_f32 v137, v228, v220
	v_mul_f32 v138, v228, v221
	v_mul_f32 v145, v2, v208
	v_fma_f32 v145, v13, v209, v145
	v_fma_f32 v145, v12, v210, v145
	v_fma_f32 v145, v8, v211, v145
	ds_read_b128 v[164:167], v5 offset:12288
	ds_read_b128 v[168:171], v5 offset:12544
	ds_read_b128 v[172:175], v5 offset:12800
	ds_read_b128 v[176:179], v5 offset:13056
	ds_read_b128 v[180:183], v5 offset:13312
	ds_read_b32 v184, v9 offset:12288
	v_add_f32_dpp v145, v145, v145 quad_perm:[1,0,3,2] row_mask:0xf bank_mask:0xf bound_ctrl:1
	v_mul_f32 v153, v2, v202
	v_fma_f32 v153, v13, v203, v153
	v_add_f32_dpp v145, v145, v145 quad_perm:[2,3,0,1] row_mask:0xf bank_mask:0xf bound_ctrl:1
	v_fma_f32 v153, v12, v204, v153
	v_fma_f32 v153, v8, v205, v153
	v_add_f32_dpp v145, v145, v145 row_half_mirror row_mask:0xf bank_mask:0xf bound_ctrl:1
	v_mul_f32 v139, v228, v222
	v_mul_f32 v140, v228, v223
	v_add_f32_dpp v145, v145, v145 row_mirror row_mask:0xf bank_mask:0xf bound_ctrl:1
	v_fma_f32 v137, -v145, v212, v137
	v_fma_f32 v138, -v145, v213, v138
	v_fma_f32 v139, -v145, v214, v139
	v_fma_f32 v140, -v145, v215, v140
	v_fma_f32 v2, v2, v216, v137
	v_fma_f32 v13, v13, v217, v138
	v_fma_f32 v12, v12, v218, v139
	v_fma_f32 v8, v8, v219, v140
	s_waitcnt lgkmcnt(6)
	v_mul_f32 v137, v250, v242
	v_mul_f32 v138, v250, v243
	v_mul_f32 v145, v2, v230
	v_fma_f32 v145, v13, v231, v145
	v_fma_f32 v145, v12, v232, v145
	v_fma_f32 v145, v8, v233, v145
	ds_read_b128 v[186:189], v5 offset:13824
	ds_read_b128 v[190:193], v5 offset:14080
	ds_read_b128 v[194:197], v5 offset:14336
	ds_read_b128 v[198:201], v5 offset:14592
	ds_read_b128 v[202:205], v5 offset:14848
	ds_read_b32 v206, v9 offset:13824
	v_add_f32_dpp v145, v145, v145 quad_perm:[1,0,3,2] row_mask:0xf bank_mask:0xf bound_ctrl:1
	v_mul_f32 v154, v2, v224
	v_fma_f32 v154, v13, v225, v154
	v_add_f32_dpp v145, v145, v145 quad_perm:[2,3,0,1] row_mask:0xf bank_mask:0xf bound_ctrl:1
	v_fma_f32 v154, v12, v226, v154
	v_fma_f32 v154, v8, v227, v154
	v_add_f32_dpp v145, v145, v145 row_half_mirror row_mask:0xf bank_mask:0xf bound_ctrl:1
	v_mul_f32 v139, v250, v244
	v_mul_f32 v140, v250, v245
	v_add_f32_dpp v145, v145, v145 row_mirror row_mask:0xf bank_mask:0xf bound_ctrl:1
	v_fma_f32 v137, -v145, v234, v137
	v_fma_f32 v138, -v145, v235, v138
	v_fma_f32 v139, -v145, v236, v139
	v_fma_f32 v140, -v145, v237, v140
	v_fma_f32 v2, v2, v238, v137
	v_fma_f32 v13, v13, v239, v138
	v_fma_f32 v12, v12, v240, v139
	v_fma_f32 v8, v8, v241, v140
	s_waitcnt lgkmcnt(6)
	v_mul_f32 v137, v184, v176
	v_mul_f32 v138, v184, v177
	v_mul_f32 v145, v2, v164
	v_fma_f32 v145, v13, v165, v145
	v_fma_f32 v145, v12, v166, v145
	v_fma_f32 v145, v8, v167, v145
	ds_read_b128 v[208:211], v5 offset:15360
	ds_read_b128 v[212:215], v5 offset:15616
	ds_read_b128 v[216:219], v5 offset:15872
	ds_read_b128 v[220:223], v5 offset:16128
	ds_read_b128 v[224:227], v5 offset:16384
	ds_read_b32 v228, v9 offset:15360
	v_add_f32_dpp v145, v145, v145 quad_perm:[1,0,3,2] row_mask:0xf bank_mask:0xf bound_ctrl:1
	v_mul_f32 v155, v2, v246
	v_fma_f32 v155, v13, v247, v155
	v_add_f32_dpp v145, v145, v145 quad_perm:[2,3,0,1] row_mask:0xf bank_mask:0xf bound_ctrl:1
	v_fma_f32 v155, v12, v248, v155
	v_fma_f32 v155, v8, v249, v155
	v_add_f32_dpp v145, v145, v145 row_half_mirror row_mask:0xf bank_mask:0xf bound_ctrl:1
	v_mul_f32 v139, v184, v178
	v_mul_f32 v140, v184, v179
	v_add_f32_dpp v145, v145, v145 row_mirror row_mask:0xf bank_mask:0xf bound_ctrl:1
	v_fma_f32 v137, -v145, v168, v137
	v_fma_f32 v138, -v145, v169, v138
	v_fma_f32 v139, -v145, v170, v139
	v_fma_f32 v140, -v145, v171, v140
	v_fma_f32 v2, v2, v172, v137
	v_fma_f32 v13, v13, v173, v138
	v_fma_f32 v12, v12, v174, v139
	v_fma_f32 v8, v8, v175, v140
	s_waitcnt lgkmcnt(6)
	v_mul_f32 v137, v206, v198
	v_mul_f32 v138, v206, v199
	v_mul_f32 v145, v2, v186
	v_fma_f32 v145, v13, v187, v145
	v_fma_f32 v145, v12, v188, v145
	v_fma_f32 v145, v8, v189, v145
	ds_read_b128 v[230:233], v5 offset:16896
	ds_read_b128 v[234:237], v5 offset:17152
	ds_read_b128 v[238:241], v5 offset:17408
	ds_read_b128 v[242:245], v5 offset:17664
	ds_read_b128 v[246:249], v5 offset:17920
	ds_read_b32 v250, v9 offset:16896
	v_add_f32_dpp v145, v145, v145 quad_perm:[1,0,3,2] row_mask:0xf bank_mask:0xf bound_ctrl:1
	v_mul_f32 v156, v2, v180
	v_fma_f32 v156, v13, v181, v156
	v_add_f32_dpp v145, v145, v145 quad_perm:[2,3,0,1] row_mask:0xf bank_mask:0xf bound_ctrl:1
	v_fma_f32 v156, v12, v182, v156
	v_fma_f32 v156, v8, v183, v156
	v_add_f32_dpp v145, v145, v145 row_half_mirror row_mask:0xf bank_mask:0xf bound_ctrl:1
	v_mul_f32 v139, v206, v200
	v_mul_f32 v140, v206, v201
	v_add_f32_dpp v145, v145, v145 row_mirror row_mask:0xf bank_mask:0xf bound_ctrl:1
	v_fma_f32 v137, -v145, v190, v137
	v_fma_f32 v138, -v145, v191, v138
	v_fma_f32 v139, -v145, v192, v139
	v_fma_f32 v140, -v145, v193, v140
	v_fma_f32 v2, v2, v194, v137
	v_fma_f32 v13, v13, v195, v138
	v_fma_f32 v12, v12, v196, v139
	v_fma_f32 v8, v8, v197, v140
	s_waitcnt lgkmcnt(6)
	v_mul_f32 v137, v228, v220
	v_mul_f32 v138, v228, v221
	v_mul_f32 v145, v2, v208
	v_fma_f32 v145, v13, v209, v145
	v_fma_f32 v145, v12, v210, v145
	v_fma_f32 v145, v8, v211, v145
	ds_read_b128 v[164:167], v5 offset:18432
	ds_read_b128 v[168:171], v5 offset:18688
	ds_read_b128 v[172:175], v5 offset:18944
	ds_read_b128 v[176:179], v5 offset:19200
	ds_read_b128 v[180:183], v5 offset:19456
	ds_read_b32 v184, v9 offset:18432
	v_add_f32_dpp v145, v145, v145 quad_perm:[1,0,3,2] row_mask:0xf bank_mask:0xf bound_ctrl:1
	v_mul_f32 v157, v2, v202
	v_fma_f32 v157, v13, v203, v157
	v_add_f32_dpp v145, v145, v145 quad_perm:[2,3,0,1] row_mask:0xf bank_mask:0xf bound_ctrl:1
	v_fma_f32 v157, v12, v204, v157
	v_fma_f32 v157, v8, v205, v157
	v_add_f32_dpp v145, v145, v145 row_half_mirror row_mask:0xf bank_mask:0xf bound_ctrl:1
	v_mul_f32 v139, v228, v222
	v_mul_f32 v140, v228, v223
	v_add_f32_dpp v145, v145, v145 row_mirror row_mask:0xf bank_mask:0xf bound_ctrl:1
	v_fma_f32 v137, -v145, v212, v137
	v_fma_f32 v138, -v145, v213, v138
	v_fma_f32 v139, -v145, v214, v139
	v_fma_f32 v140, -v145, v215, v140
	v_fma_f32 v2, v2, v216, v137
	v_fma_f32 v13, v13, v217, v138
	v_fma_f32 v12, v12, v218, v139
	v_fma_f32 v8, v8, v219, v140
	s_waitcnt lgkmcnt(6)
	v_mul_f32 v137, v250, v242
	v_mul_f32 v138, v250, v243
	v_mul_f32 v145, v2, v230
	v_fma_f32 v145, v13, v231, v145
	v_fma_f32 v145, v12, v232, v145
	v_fma_f32 v145, v8, v233, v145
	ds_read_b128 v[186:189], v5 offset:19968
	ds_read_b128 v[190:193], v5 offset:20224
	ds_read_b128 v[194:197], v5 offset:20480
	ds_read_b128 v[198:201], v5 offset:20736
	ds_read_b128 v[202:205], v5 offset:20992
	ds_read_b32 v206, v9 offset:19968
	v_add_f32_dpp v145, v145, v145 quad_perm:[1,0,3,2] row_mask:0xf bank_mask:0xf bound_ctrl:1
	v_mul_f32 v158, v2, v224
	v_fma_f32 v158, v13, v225, v158
	v_add_f32_dpp v145, v145, v145 quad_perm:[2,3,0,1] row_mask:0xf bank_mask:0xf bound_ctrl:1
	v_fma_f32 v158, v12, v226, v158
	v_fma_f32 v158, v8, v227, v158
	v_add_f32_dpp v145, v145, v145 row_half_mirror row_mask:0xf bank_mask:0xf bound_ctrl:1
	v_mul_f32 v139, v250, v244
	v_mul_f32 v140, v250, v245
	v_add_f32_dpp v145, v145, v145 row_mirror row_mask:0xf bank_mask:0xf bound_ctrl:1
	v_fma_f32 v137, -v145, v234, v137
	v_fma_f32 v138, -v145, v235, v138
	v_fma_f32 v139, -v145, v236, v139
	v_fma_f32 v140, -v145, v237, v140
	v_fma_f32 v2, v2, v238, v137
	v_fma_f32 v13, v13, v239, v138
	v_fma_f32 v12, v12, v240, v139
	v_fma_f32 v8, v8, v241, v140
	s_waitcnt lgkmcnt(6)
	v_mul_f32 v137, v184, v176
	v_mul_f32 v138, v184, v177
	v_mul_f32 v145, v2, v164
	v_fma_f32 v145, v13, v165, v145
	v_fma_f32 v145, v12, v166, v145
	v_fma_f32 v145, v8, v167, v145
	ds_read_b128 v[208:211], v5 offset:21504
	ds_read_b128 v[212:215], v5 offset:21760
	ds_read_b128 v[216:219], v5 offset:22016
	ds_read_b128 v[220:223], v5 offset:22272
	ds_read_b128 v[224:227], v5 offset:22528
	ds_read_b32 v228, v9 offset:21504
	v_add_f32_dpp v145, v145, v145 quad_perm:[1,0,3,2] row_mask:0xf bank_mask:0xf bound_ctrl:1
	v_mul_f32 v159, v2, v246
	v_fma_f32 v159, v13, v247, v159
	v_add_f32_dpp v145, v145, v145 quad_perm:[2,3,0,1] row_mask:0xf bank_mask:0xf bound_ctrl:1
	v_fma_f32 v159, v12, v248, v159
	v_fma_f32 v159, v8, v249, v159
	v_add_f32_dpp v145, v145, v145 row_half_mirror row_mask:0xf bank_mask:0xf bound_ctrl:1
	v_mul_f32 v139, v184, v178
	v_mul_f32 v140, v184, v179
	v_add_f32_dpp v145, v145, v145 row_mirror row_mask:0xf bank_mask:0xf bound_ctrl:1
	v_fma_f32 v137, -v145, v168, v137
	v_fma_f32 v138, -v145, v169, v138
	v_fma_f32 v139, -v145, v170, v139
	v_fma_f32 v140, -v145, v171, v140
	v_fma_f32 v2, v2, v172, v137
	v_fma_f32 v13, v13, v173, v138
	v_fma_f32 v12, v12, v174, v139
	v_fma_f32 v8, v8, v175, v140
	s_waitcnt lgkmcnt(6)
	v_mul_f32 v137, v206, v198
	v_mul_f32 v138, v206, v199
	v_mul_f32 v145, v2, v186
	v_fma_f32 v145, v13, v187, v145
	v_fma_f32 v145, v12, v188, v145
	v_fma_f32 v145, v8, v189, v145
	ds_read_b128 v[230:233], v5 offset:23040
	ds_read_b128 v[234:237], v5 offset:23296
	ds_read_b128 v[238:241], v5 offset:23552
	ds_read_b128 v[242:245], v5 offset:23808
	ds_read_b128 v[246:249], v5 offset:24064
	ds_read_b32 v250, v9 offset:23040
	v_add_f32_dpp v145, v145, v145 quad_perm:[1,0,3,2] row_mask:0xf bank_mask:0xf bound_ctrl:1
	v_mul_f32 v160, v2, v180
	v_fma_f32 v160, v13, v181, v160
	v_add_f32_dpp v145, v145, v145 quad_perm:[2,3,0,1] row_mask:0xf bank_mask:0xf bound_ctrl:1
	v_fma_f32 v160, v12, v182, v160
	v_fma_f32 v160, v8, v183, v160
	v_add_f32_dpp v145, v145, v145 row_half_mirror row_mask:0xf bank_mask:0xf bound_ctrl:1
	v_mul_f32 v139, v206, v200
	v_mul_f32 v140, v206, v201
	v_add_f32_dpp v145, v145, v145 row_mirror row_mask:0xf bank_mask:0xf bound_ctrl:1
	v_fma_f32 v137, -v145, v190, v137
	v_fma_f32 v138, -v145, v191, v138
	v_fma_f32 v139, -v145, v192, v139
	v_fma_f32 v140, -v145, v193, v140
	v_fma_f32 v2, v2, v194, v137
	v_fma_f32 v13, v13, v195, v138
	v_fma_f32 v12, v12, v196, v139
	v_fma_f32 v8, v8, v197, v140
	s_waitcnt lgkmcnt(6)
	v_mul_f32 v137, v228, v220
	v_mul_f32 v138, v228, v221
	v_mul_f32 v145, v2, v208
	v_fma_f32 v145, v13, v209, v145
	v_fma_f32 v145, v12, v210, v145
	v_fma_f32 v145, v8, v211, v145
	ds_read_b128 v[164:167], v5 offset:24576
	ds_read_b128 v[168:171], v5 offset:24832
	ds_read_b128 v[172:175], v5 offset:25088
	ds_read_b128 v[176:179], v5 offset:25344
	ds_read_b128 v[180:183], v5 offset:25600
	ds_read_b32 v184, v9 offset:24576
	v_add_f32_dpp v145, v145, v145 quad_perm:[1,0,3,2] row_mask:0xf bank_mask:0xf bound_ctrl:1
	v_mul_f32 v161, v2, v202
	v_fma_f32 v161, v13, v203, v161
	v_add_f32_dpp v145, v145, v145 quad_perm:[2,3,0,1] row_mask:0xf bank_mask:0xf bound_ctrl:1
	v_fma_f32 v161, v12, v204, v161
	v_fma_f32 v161, v8, v205, v161
	v_add_f32_dpp v145, v145, v145 row_half_mirror row_mask:0xf bank_mask:0xf bound_ctrl:1
	v_mul_f32 v139, v228, v222
	v_mul_f32 v140, v228, v223
	v_add_f32_dpp v145, v145, v145 row_mirror row_mask:0xf bank_mask:0xf bound_ctrl:1
	v_fma_f32 v137, -v145, v212, v137
	v_fma_f32 v138, -v145, v213, v138
	v_fma_f32 v139, -v145, v214, v139
	v_fma_f32 v140, -v145, v215, v140
	v_fma_f32 v2, v2, v216, v137
	v_fma_f32 v13, v13, v217, v138
	v_fma_f32 v12, v12, v218, v139
	v_fma_f32 v8, v8, v219, v140
	s_waitcnt lgkmcnt(6)
	v_mul_f32 v137, v250, v242
	v_mul_f32 v138, v250, v243
	v_mul_f32 v145, v2, v230
	v_fma_f32 v145, v13, v231, v145
	v_fma_f32 v145, v12, v232, v145
	v_fma_f32 v145, v8, v233, v145
	ds_read_b128 v[186:189], v5 offset:26112
	ds_read_b128 v[190:193], v5 offset:26368
	ds_read_b128 v[194:197], v5 offset:26624
	ds_read_b128 v[198:201], v5 offset:26880
	ds_read_b128 v[202:205], v5 offset:27136
	ds_read_b32 v206, v9 offset:26112
	v_add_f32_dpp v145, v145, v145 quad_perm:[1,0,3,2] row_mask:0xf bank_mask:0xf bound_ctrl:1
	v_mul_f32 v162, v2, v224
	v_fma_f32 v162, v13, v225, v162
	v_add_f32_dpp v145, v145, v145 quad_perm:[2,3,0,1] row_mask:0xf bank_mask:0xf bound_ctrl:1
	v_fma_f32 v162, v12, v226, v162
	v_fma_f32 v162, v8, v227, v162
	v_add_f32_dpp v145, v145, v145 row_half_mirror row_mask:0xf bank_mask:0xf bound_ctrl:1
	v_mul_f32 v139, v250, v244
	v_mul_f32 v140, v250, v245
	v_add_f32_dpp v145, v145, v145 row_mirror row_mask:0xf bank_mask:0xf bound_ctrl:1
	v_fma_f32 v137, -v145, v234, v137
	v_fma_f32 v138, -v145, v235, v138
	v_fma_f32 v139, -v145, v236, v139
	v_fma_f32 v140, -v145, v237, v140
	v_fma_f32 v2, v2, v238, v137
	v_fma_f32 v13, v13, v239, v138
	v_fma_f32 v12, v12, v240, v139
	v_fma_f32 v8, v8, v241, v140
	s_waitcnt lgkmcnt(6)
	v_mul_f32 v137, v184, v176
	v_mul_f32 v138, v184, v177
	v_mul_f32 v145, v2, v164
	v_fma_f32 v145, v13, v165, v145
	v_fma_f32 v145, v12, v166, v145
	v_fma_f32 v145, v8, v167, v145
	ds_read_b128 v[208:211], v5 offset:27648
	ds_read_b128 v[212:215], v5 offset:27904
	ds_read_b128 v[216:219], v5 offset:28160
	ds_read_b128 v[220:223], v5 offset:28416
	ds_read_b128 v[224:227], v5 offset:28672
	ds_read_b32 v228, v9 offset:27648
	v_add_f32_dpp v145, v145, v145 quad_perm:[1,0,3,2] row_mask:0xf bank_mask:0xf bound_ctrl:1
	v_mul_f32 v163, v2, v246
	v_fma_f32 v163, v13, v247, v163
	v_add_f32_dpp v145, v145, v145 quad_perm:[2,3,0,1] row_mask:0xf bank_mask:0xf bound_ctrl:1
	v_fma_f32 v163, v12, v248, v163
	v_fma_f32 v163, v8, v249, v163
	v_add_f32_dpp v145, v145, v145 row_half_mirror row_mask:0xf bank_mask:0xf bound_ctrl:1
	v_mul_f32 v139, v184, v178
	v_mul_f32 v140, v184, v179
	v_add_f32_dpp v145, v145, v145 row_mirror row_mask:0xf bank_mask:0xf bound_ctrl:1
	v_fma_f32 v137, -v145, v168, v137
	v_fma_f32 v138, -v145, v169, v138
	v_fma_f32 v139, -v145, v170, v139
	v_fma_f32 v140, -v145, v171, v140
	v_fma_f32 v2, v2, v172, v137
	v_fma_f32 v13, v13, v173, v138
	v_fma_f32 v12, v12, v174, v139
	v_fma_f32 v8, v8, v175, v140
	s_waitcnt lgkmcnt(6)
	v_mul_f32 v137, v206, v198
	v_mul_f32 v138, v206, v199
	v_mul_f32 v145, v2, v186
	v_fma_f32 v145, v13, v187, v145
	v_fma_f32 v145, v12, v188, v145
	v_fma_f32 v145, v8, v189, v145
	v_and_b32 v244, 8, v3
	v_cmp_ne_u32 vcc, 0, v244
	v_cndmask_b32 v244, v156, v148, vcc
	v_cndmask_b32 v245, v157, v149, vcc
	v_cndmask_b32 v246, v158, v150, vcc
	v_cndmask_b32 v247, v159, v151, vcc
	v_cndmask_b32 v230, v148, v156, vcc
	v_cndmask_b32 v231, v149, v157, vcc
	v_cndmask_b32 v232, v150, v158, vcc
	v_cndmask_b32 v233, v151, v159, vcc
	v_add_f32_dpp v230, v244, v230 row_mirror row_mask:0xf bank_mask:0xf bound_ctrl:1
	v_add_f32_dpp v231, v245, v231 row_mirror row_mask:0xf bank_mask:0xf bound_ctrl:1
	v_add_f32_dpp v232, v246, v232 row_mirror row_mask:0xf bank_mask:0xf bound_ctrl:1
	v_add_f32_dpp v233, v247, v233 row_mirror row_mask:0xf bank_mask:0xf bound_ctrl:1
	v_cndmask_b32 v244, v160, v152, vcc
	v_cndmask_b32 v245, v161, v153, vcc
	v_cndmask_b32 v246, v162, v154, vcc
	v_cndmask_b32 v247, v163, v155, vcc
	v_cndmask_b32 v234, v152, v160, vcc
	v_cndmask_b32 v235, v153, v161, vcc
	v_cndmask_b32 v236, v154, v162, vcc
	v_cndmask_b32 v237, v155, v163, vcc
	v_add_f32_dpp v234, v244, v234 row_mirror row_mask:0xf bank_mask:0xf bound_ctrl:1
	v_add_f32_dpp v235, v245, v235 row_mirror row_mask:0xf bank_mask:0xf bound_ctrl:1
	v_add_f32_dpp v236, v246, v236 row_mirror row_mask:0xf bank_mask:0xf bound_ctrl:1
	v_add_f32_dpp v237, v247, v237 row_mirror row_mask:0xf bank_mask:0xf bound_ctrl:1
	v_and_b32 v244, 4, v3
	v_cmp_ne_u32 vcc, 0, v244
	v_cndmask_b32 v244, v234, v230, vcc
	v_cndmask_b32 v245, v235, v231, vcc
	v_cndmask_b32 v246, v236, v232, vcc
	v_cndmask_b32 v247, v237, v233, vcc
	v_cndmask_b32 v238, v230, v234, vcc
	v_cndmask_b32 v239, v231, v235, vcc
	v_cndmask_b32 v240, v232, v236, vcc
	v_cndmask_b32 v241, v233, v237, vcc
	v_add_f32_dpp v238, v244, v238 row_half_mirror row_mask:0xf bank_mask:0xf bound_ctrl:1
	v_add_f32_dpp v239, v245, v239 row_half_mirror row_mask:0xf bank_mask:0xf bound_ctrl:1
	v_add_f32_dpp v240, v246, v240 row_half_mirror row_mask:0xf bank_mask:0xf bound_ctrl:1
	v_add_f32_dpp v241, v247, v241 row_half_mirror row_mask:0xf bank_mask:0xf bound_ctrl:1
	v_and_b32 v244, 2, v3
	v_cmp_ne_u32 vcc, 0, v244
	v_cndmask_b32 v244, v240, v238, vcc
	v_cndmask_b32 v245, v241, v239, vcc
	v_cndmask_b32 v242, v238, v240, vcc
	v_cndmask_b32 v243, v239, v241, vcc
	v_add_f32_dpp v242, v244, v242 quad_perm:[2,3,0,1] row_mask:0xf bank_mask:0xf bound_ctrl:1
	v_add_f32_dpp v243, v245, v243 quad_perm:[2,3,0,1] row_mask:0xf bank_mask:0xf bound_ctrl:1
	v_and_b32 v244, 1, v3
	v_cmp_ne_u32 vcc, 0, v244
	v_cndmask_b32 v244, v243, v242, vcc
	v_cndmask_b32 v245, v242, v243, vcc
	s_nop 0
	v_add_f32_dpp v18, v244, v245 quad_perm:[1,0,3,2] row_mask:0xf bank_mask:0xf bound_ctrl:1
	ds_read_b128 v[230:233], v5 offset:29184
	ds_read_b128 v[234:237], v5 offset:29440
	ds_read_b128 v[238:241], v5 offset:29696
	ds_read_b128 v[242:245], v5 offset:29952
	ds_read_b128 v[246:249], v5 offset:30208
	ds_read_b32 v250, v9 offset:29184
	v_add_f32_dpp v145, v145, v145 quad_perm:[1,0,3,2] row_mask:0xf bank_mask:0xf bound_ctrl:1
	v_mul_f32 v148, v2, v180
	v_fma_f32 v148, v13, v181, v148
	v_add_f32_dpp v145, v145, v145 quad_perm:[2,3,0,1] row_mask:0xf bank_mask:0xf bound_ctrl:1
	v_fma_f32 v148, v12, v182, v148
	v_fma_f32 v148, v8, v183, v148
	v_add_f32_dpp v145, v145, v145 row_half_mirror row_mask:0xf bank_mask:0xf bound_ctrl:1
	v_mul_f32 v139, v206, v200
	v_mul_f32 v140, v206, v201
	v_add_f32_dpp v145, v145, v145 row_mirror row_mask:0xf bank_mask:0xf bound_ctrl:1
	v_fma_f32 v137, -v145, v190, v137
	v_fma_f32 v138, -v145, v191, v138
	v_fma_f32 v139, -v145, v192, v139
	v_fma_f32 v140, -v145, v193, v140
	v_fma_f32 v2, v2, v194, v137
	v_fma_f32 v13, v13, v195, v138
	v_fma_f32 v12, v12, v196, v139
	v_fma_f32 v8, v8, v197, v140
	s_waitcnt lgkmcnt(6)
	v_mul_f32 v137, v228, v220
	v_mul_f32 v138, v228, v221
	v_mul_f32 v145, v2, v208
	v_fma_f32 v145, v13, v209, v145
	v_fma_f32 v145, v12, v210, v145
	v_fma_f32 v145, v8, v211, v145
	ds_read_b128 v[164:167], v5 offset:30720
	ds_read_b128 v[168:171], v5 offset:30976
	ds_read_b128 v[172:175], v5 offset:31232
	ds_read_b128 v[176:179], v5 offset:31488
	ds_read_b128 v[180:183], v5 offset:31744
	ds_read_b32 v184, v9 offset:30720
	v_add_f32_dpp v145, v145, v145 quad_perm:[1,0,3,2] row_mask:0xf bank_mask:0xf bound_ctrl:1
	v_mul_f32 v149, v2, v202
	v_fma_f32 v149, v13, v203, v149
	v_add_f32_dpp v145, v145, v145 quad_perm:[2,3,0,1] row_mask:0xf bank_mask:0xf bound_ctrl:1
	v_fma_f32 v149, v12, v204, v149
	v_fma_f32 v149, v8, v205, v149
	v_add_f32_dpp v145, v145, v145 row_half_mirror row_mask:0xf bank_mask:0xf bound_ctrl:1
	v_mul_f32 v139, v228, v222
	v_mul_f32 v140, v228, v223
	v_add_f32_dpp v145, v145, v145 row_mirror row_mask:0xf bank_mask:0xf bound_ctrl:1
	v_fma_f32 v137, -v145, v212, v137
	v_fma_f32 v138, -v145, v213, v138
	v_fma_f32 v139, -v145, v214, v139
	v_fma_f32 v140, -v145, v215, v140
	v_fma_f32 v2, v2, v216, v137
	v_fma_f32 v13, v13, v217, v138
	v_fma_f32 v12, v12, v218, v139
	v_fma_f32 v8, v8, v219, v140
	s_waitcnt lgkmcnt(6)
	v_mul_f32 v137, v250, v242
	v_mul_f32 v138, v250, v243
	v_mul_f32 v145, v2, v230
	v_fma_f32 v145, v13, v231, v145
	v_fma_f32 v145, v12, v232, v145
	v_fma_f32 v145, v8, v233, v145
	ds_read_b128 v[186:189], v5 offset:32256
	ds_read_b128 v[190:193], v5 offset:32512
	ds_read_b128 v[194:197], v5 offset:32768
	ds_read_b128 v[198:201], v5 offset:33024
	ds_read_b128 v[202:205], v5 offset:33280
	ds_read_b32 v206, v9 offset:32256
	v_add_f32_dpp v145, v145, v145 quad_perm:[1,0,3,2] row_mask:0xf bank_mask:0xf bound_ctrl:1
	v_mul_f32 v150, v2, v224
	v_fma_f32 v150, v13, v225, v150
	v_add_f32_dpp v145, v145, v145 quad_perm:[2,3,0,1] row_mask:0xf bank_mask:0xf bound_ctrl:1
	v_fma_f32 v150, v12, v226, v150
	v_fma_f32 v150, v8, v227, v150
	v_add_f32_dpp v145, v145, v145 row_half_mirror row_mask:0xf bank_mask:0xf bound_ctrl:1
	v_mul_f32 v139, v250, v244
	v_mul_f32 v140, v250, v245
	v_add_f32_dpp v145, v145, v145 row_mirror row_mask:0xf bank_mask:0xf bound_ctrl:1
	v_fma_f32 v137, -v145, v234, v137
	v_fma_f32 v138, -v145, v235, v138
	v_fma_f32 v139, -v145, v236, v139
	v_fma_f32 v140, -v145, v237, v140
	v_fma_f32 v2, v2, v238, v137
	v_fma_f32 v13, v13, v239, v138
	v_fma_f32 v12, v12, v240, v139
	v_fma_f32 v8, v8, v241, v140
	s_waitcnt lgkmcnt(6)
	v_mul_f32 v137, v184, v176
	v_mul_f32 v138, v184, v177
	v_mul_f32 v145, v2, v164
	v_fma_f32 v145, v13, v165, v145
	v_fma_f32 v145, v12, v166, v145
	v_fma_f32 v145, v8, v167, v145
	ds_read_b128 v[208:211], v5 offset:33792
	ds_read_b128 v[212:215], v5 offset:34048
	ds_read_b128 v[216:219], v5 offset:34304
	ds_read_b128 v[220:223], v5 offset:34560
	ds_read_b128 v[224:227], v5 offset:34816
	ds_read_b32 v228, v9 offset:33792
	v_add_f32_dpp v145, v145, v145 quad_perm:[1,0,3,2] row_mask:0xf bank_mask:0xf bound_ctrl:1
	v_mul_f32 v151, v2, v246
	v_fma_f32 v151, v13, v247, v151
	v_add_f32_dpp v145, v145, v145 quad_perm:[2,3,0,1] row_mask:0xf bank_mask:0xf bound_ctrl:1
	v_fma_f32 v151, v12, v248, v151
	v_fma_f32 v151, v8, v249, v151
	v_add_f32_dpp v145, v145, v145 row_half_mirror row_mask:0xf bank_mask:0xf bound_ctrl:1
	v_mul_f32 v139, v184, v178
	v_mul_f32 v140, v184, v179
	v_add_f32_dpp v145, v145, v145 row_mirror row_mask:0xf bank_mask:0xf bound_ctrl:1
	v_fma_f32 v137, -v145, v168, v137
	v_fma_f32 v138, -v145, v169, v138
	v_fma_f32 v139, -v145, v170, v139
	v_fma_f32 v140, -v145, v171, v140
	v_fma_f32 v2, v2, v172, v137
	v_fma_f32 v13, v13, v173, v138
	v_fma_f32 v12, v12, v174, v139
	v_fma_f32 v8, v8, v175, v140
	s_waitcnt lgkmcnt(6)
	v_mul_f32 v137, v206, v198
	v_mul_f32 v138, v206, v199
	v_mul_f32 v145, v2, v186
	v_fma_f32 v145, v13, v187, v145
	v_fma_f32 v145, v12, v188, v145
	v_fma_f32 v145, v8, v189, v145
	ds_read_b128 v[230:233], v5 offset:35328
	ds_read_b128 v[234:237], v5 offset:35584
	ds_read_b128 v[238:241], v5 offset:35840
	ds_read_b128 v[242:245], v5 offset:36096
	ds_read_b128 v[246:249], v5 offset:36352
	ds_read_b32 v250, v9 offset:35328
	v_add_f32_dpp v145, v145, v145 quad_perm:[1,0,3,2] row_mask:0xf bank_mask:0xf bound_ctrl:1
	v_mul_f32 v152, v2, v180
	v_fma_f32 v152, v13, v181, v152
	v_add_f32_dpp v145, v145, v145 quad_perm:[2,3,0,1] row_mask:0xf bank_mask:0xf bound_ctrl:1
	v_fma_f32 v152, v12, v182, v152
	v_fma_f32 v152, v8, v183, v152
	v_add_f32_dpp v145, v145, v145 row_half_mirror row_mask:0xf bank_mask:0xf bound_ctrl:1
	v_mul_f32 v139, v206, v200
	v_mul_f32 v140, v206, v201
	v_add_f32_dpp v145, v145, v145 row_mirror row_mask:0xf bank_mask:0xf bound_ctrl:1
	v_fma_f32 v137, -v145, v190, v137
	v_fma_f32 v138, -v145, v191, v138
	v_fma_f32 v139, -v145, v192, v139
	v_fma_f32 v140, -v145, v193, v140
	v_fma_f32 v2, v2, v194, v137
	v_fma_f32 v13, v13, v195, v138
	v_fma_f32 v12, v12, v196, v139
	v_fma_f32 v8, v8, v197, v140
	s_waitcnt lgkmcnt(6)
	v_mul_f32 v137, v228, v220
	v_mul_f32 v138, v228, v221
	v_mul_f32 v145, v2, v208
	v_fma_f32 v145, v13, v209, v145
	v_fma_f32 v145, v12, v210, v145
	v_fma_f32 v145, v8, v211, v145
	ds_read_b128 v[164:167], v5 offset:36864
	ds_read_b128 v[168:171], v5 offset:37120
	ds_read_b128 v[172:175], v5 offset:37376
	ds_read_b128 v[176:179], v5 offset:37632
	ds_read_b128 v[180:183], v5 offset:37888
	ds_read_b32 v184, v9 offset:36864
	v_add_f32_dpp v145, v145, v145 quad_perm:[1,0,3,2] row_mask:0xf bank_mask:0xf bound_ctrl:1
	v_mul_f32 v153, v2, v202
	v_fma_f32 v153, v13, v203, v153
	v_add_f32_dpp v145, v145, v145 quad_perm:[2,3,0,1] row_mask:0xf bank_mask:0xf bound_ctrl:1
	v_fma_f32 v153, v12, v204, v153
	v_fma_f32 v153, v8, v205, v153
	v_add_f32_dpp v145, v145, v145 row_half_mirror row_mask:0xf bank_mask:0xf bound_ctrl:1
	v_mul_f32 v139, v228, v222
	v_mul_f32 v140, v228, v223
	v_add_f32_dpp v145, v145, v145 row_mirror row_mask:0xf bank_mask:0xf bound_ctrl:1
	v_fma_f32 v137, -v145, v212, v137
	v_fma_f32 v138, -v145, v213, v138
	v_fma_f32 v139, -v145, v214, v139
	v_fma_f32 v140, -v145, v215, v140
	v_fma_f32 v2, v2, v216, v137
	v_fma_f32 v13, v13, v217, v138
	v_fma_f32 v12, v12, v218, v139
	v_fma_f32 v8, v8, v219, v140
	s_waitcnt lgkmcnt(6)
	v_mul_f32 v137, v250, v242
	v_mul_f32 v138, v250, v243
	v_mul_f32 v145, v2, v230
	v_fma_f32 v145, v13, v231, v145
	v_fma_f32 v145, v12, v232, v145
	v_fma_f32 v145, v8, v233, v145
	ds_read_b128 v[186:189], v5 offset:38400
	ds_read_b128 v[190:193], v5 offset:38656
	ds_read_b128 v[194:197], v5 offset:38912
	ds_read_b128 v[198:201], v5 offset:39168
	ds_read_b128 v[202:205], v5 offset:39424
	ds_read_b32 v206, v9 offset:38400
	v_add_f32_dpp v145, v145, v145 quad_perm:[1,0,3,2] row_mask:0xf bank_mask:0xf bound_ctrl:1
	v_mul_f32 v154, v2, v224
	v_fma_f32 v154, v13, v225, v154
	v_add_f32_dpp v145, v145, v145 quad_perm:[2,3,0,1] row_mask:0xf bank_mask:0xf bound_ctrl:1
	v_fma_f32 v154, v12, v226, v154
	v_fma_f32 v154, v8, v227, v154
	v_add_f32_dpp v145, v145, v145 row_half_mirror row_mask:0xf bank_mask:0xf bound_ctrl:1
	v_mul_f32 v139, v250, v244
	v_mul_f32 v140, v250, v245
	v_add_f32_dpp v145, v145, v145 row_mirror row_mask:0xf bank_mask:0xf bound_ctrl:1
	v_fma_f32 v137, -v145, v234, v137
	v_fma_f32 v138, -v145, v235, v138
	v_fma_f32 v139, -v145, v236, v139
	v_fma_f32 v140, -v145, v237, v140
	v_fma_f32 v2, v2, v238, v137
	v_fma_f32 v13, v13, v239, v138
	v_fma_f32 v12, v12, v240, v139
	v_fma_f32 v8, v8, v241, v140
	s_waitcnt lgkmcnt(6)
	v_mul_f32 v137, v184, v176
	v_mul_f32 v138, v184, v177
	v_mul_f32 v145, v2, v164
	v_fma_f32 v145, v13, v165, v145
	v_fma_f32 v145, v12, v166, v145
	v_fma_f32 v145, v8, v167, v145
	ds_read_b128 v[208:211], v5 offset:39936
	ds_read_b128 v[212:215], v5 offset:40192
	ds_read_b128 v[216:219], v5 offset:40448
	ds_read_b128 v[220:223], v5 offset:40704
	ds_read_b128 v[224:227], v5 offset:40960
	ds_read_b32 v228, v9 offset:39936
	v_add_f32_dpp v145, v145, v145 quad_perm:[1,0,3,2] row_mask:0xf bank_mask:0xf bound_ctrl:1
	v_mul_f32 v155, v2, v246
	v_fma_f32 v155, v13, v247, v155
	v_add_f32_dpp v145, v145, v145 quad_perm:[2,3,0,1] row_mask:0xf bank_mask:0xf bound_ctrl:1
	v_fma_f32 v155, v12, v248, v155
	v_fma_f32 v155, v8, v249, v155
	v_add_f32_dpp v145, v145, v145 row_half_mirror row_mask:0xf bank_mask:0xf bound_ctrl:1
	v_mul_f32 v139, v184, v178
	v_mul_f32 v140, v184, v179
	v_add_f32_dpp v145, v145, v145 row_mirror row_mask:0xf bank_mask:0xf bound_ctrl:1
	v_fma_f32 v137, -v145, v168, v137
	v_fma_f32 v138, -v145, v169, v138
	v_fma_f32 v139, -v145, v170, v139
	v_fma_f32 v140, -v145, v171, v140
	v_fma_f32 v2, v2, v172, v137
	v_fma_f32 v13, v13, v173, v138
	v_fma_f32 v12, v12, v174, v139
	v_fma_f32 v8, v8, v175, v140
	s_waitcnt lgkmcnt(6)
	v_mul_f32 v137, v206, v198
	v_mul_f32 v138, v206, v199
	v_mul_f32 v145, v2, v186
	v_fma_f32 v145, v13, v187, v145
	v_fma_f32 v145, v12, v188, v145
	v_fma_f32 v145, v8, v189, v145
	ds_read_b128 v[230:233], v5 offset:41472
	ds_read_b128 v[234:237], v5 offset:41728
	ds_read_b128 v[238:241], v5 offset:41984
	ds_read_b128 v[242:245], v5 offset:42240
	ds_read_b128 v[246:249], v5 offset:42496
	ds_read_b32 v250, v9 offset:41472
	v_add_f32_dpp v145, v145, v145 quad_perm:[1,0,3,2] row_mask:0xf bank_mask:0xf bound_ctrl:1
	v_mul_f32 v156, v2, v180
	v_fma_f32 v156, v13, v181, v156
	v_add_f32_dpp v145, v145, v145 quad_perm:[2,3,0,1] row_mask:0xf bank_mask:0xf bound_ctrl:1
	v_fma_f32 v156, v12, v182, v156
	v_fma_f32 v156, v8, v183, v156
	v_add_f32_dpp v145, v145, v145 row_half_mirror row_mask:0xf bank_mask:0xf bound_ctrl:1
	v_mul_f32 v139, v206, v200
	v_mul_f32 v140, v206, v201
	v_add_f32_dpp v145, v145, v145 row_mirror row_mask:0xf bank_mask:0xf bound_ctrl:1
	v_fma_f32 v137, -v145, v190, v137
	v_fma_f32 v138, -v145, v191, v138
	v_fma_f32 v139, -v145, v192, v139
	v_fma_f32 v140, -v145, v193, v140
	v_fma_f32 v2, v2, v194, v137
	v_fma_f32 v13, v13, v195, v138
	v_fma_f32 v12, v12, v196, v139
	v_fma_f32 v8, v8, v197, v140
	s_waitcnt lgkmcnt(6)
	v_mul_f32 v137, v228, v220
	v_mul_f32 v138, v228, v221
	v_mul_f32 v145, v2, v208
	v_fma_f32 v145, v13, v209, v145
	v_fma_f32 v145, v12, v210, v145
	v_fma_f32 v145, v8, v211, v145
	ds_read_b128 v[164:167], v5 offset:43008
	ds_read_b128 v[168:171], v5 offset:43264
	ds_read_b128 v[172:175], v5 offset:43520
	ds_read_b128 v[176:179], v5 offset:43776
	ds_read_b128 v[180:183], v5 offset:44032
	ds_read_b32 v184, v9 offset:43008
	v_add_f32_dpp v145, v145, v145 quad_perm:[1,0,3,2] row_mask:0xf bank_mask:0xf bound_ctrl:1
	v_mul_f32 v157, v2, v202
	v_fma_f32 v157, v13, v203, v157
	v_add_f32_dpp v145, v145, v145 quad_perm:[2,3,0,1] row_mask:0xf bank_mask:0xf bound_ctrl:1
	v_fma_f32 v157, v12, v204, v157
	v_fma_f32 v157, v8, v205, v157
	v_add_f32_dpp v145, v145, v145 row_half_mirror row_mask:0xf bank_mask:0xf bound_ctrl:1
	v_mul_f32 v139, v228, v222
	v_mul_f32 v140, v228, v223
	v_add_f32_dpp v145, v145, v145 row_mirror row_mask:0xf bank_mask:0xf bound_ctrl:1
	v_fma_f32 v137, -v145, v212, v137
	v_fma_f32 v138, -v145, v213, v138
	v_fma_f32 v139, -v145, v214, v139
	v_fma_f32 v140, -v145, v215, v140
	v_fma_f32 v2, v2, v216, v137
	v_fma_f32 v13, v13, v217, v138
	v_fma_f32 v12, v12, v218, v139
	v_fma_f32 v8, v8, v219, v140
	s_waitcnt lgkmcnt(6)
	v_mul_f32 v137, v250, v242
	v_mul_f32 v138, v250, v243
	v_mul_f32 v145, v2, v230
	v_fma_f32 v145, v13, v231, v145
	v_fma_f32 v145, v12, v232, v145
	v_fma_f32 v145, v8, v233, v145
	ds_read_b128 v[186:189], v5 offset:44544
	ds_read_b128 v[190:193], v5 offset:44800
	ds_read_b128 v[194:197], v5 offset:45056
	ds_read_b128 v[198:201], v5 offset:45312
	ds_read_b128 v[202:205], v5 offset:45568
	ds_read_b32 v206, v9 offset:44544
	v_add_f32_dpp v145, v145, v145 quad_perm:[1,0,3,2] row_mask:0xf bank_mask:0xf bound_ctrl:1
	v_mul_f32 v158, v2, v224
	v_fma_f32 v158, v13, v225, v158
	v_add_f32_dpp v145, v145, v145 quad_perm:[2,3,0,1] row_mask:0xf bank_mask:0xf bound_ctrl:1
	v_fma_f32 v158, v12, v226, v158
	v_fma_f32 v158, v8, v227, v158
	v_add_f32_dpp v145, v145, v145 row_half_mirror row_mask:0xf bank_mask:0xf bound_ctrl:1
	v_mul_f32 v139, v250, v244
	v_mul_f32 v140, v250, v245
	v_add_f32_dpp v145, v145, v145 row_mirror row_mask:0xf bank_mask:0xf bound_ctrl:1
	v_fma_f32 v137, -v145, v234, v137
	v_fma_f32 v138, -v145, v235, v138
	v_fma_f32 v139, -v145, v236, v139
	v_fma_f32 v140, -v145, v237, v140
	v_fma_f32 v2, v2, v238, v137
	v_fma_f32 v13, v13, v239, v138
	v_fma_f32 v12, v12, v240, v139
	v_fma_f32 v8, v8, v241, v140
	s_waitcnt lgkmcnt(6)
	v_mul_f32 v137, v184, v176
	v_mul_f32 v138, v184, v177
	v_mul_f32 v145, v2, v164
	v_fma_f32 v145, v13, v165, v145
	v_fma_f32 v145, v12, v166, v145
	v_fma_f32 v145, v8, v167, v145
	ds_read_b128 v[208:211], v5 offset:46080
	ds_read_b128 v[212:215], v5 offset:46336
	ds_read_b128 v[216:219], v5 offset:46592
	ds_read_b128 v[220:223], v5 offset:46848
	ds_read_b128 v[224:227], v5 offset:47104
	ds_read_b32 v228, v9 offset:46080
	v_add_f32_dpp v145, v145, v145 quad_perm:[1,0,3,2] row_mask:0xf bank_mask:0xf bound_ctrl:1
	v_mul_f32 v159, v2, v246
	v_fma_f32 v159, v13, v247, v159
	v_add_f32_dpp v145, v145, v145 quad_perm:[2,3,0,1] row_mask:0xf bank_mask:0xf bound_ctrl:1
	v_fma_f32 v159, v12, v248, v159
	v_fma_f32 v159, v8, v249, v159
	v_add_f32_dpp v145, v145, v145 row_half_mirror row_mask:0xf bank_mask:0xf bound_ctrl:1
	v_mul_f32 v139, v184, v178
	v_mul_f32 v140, v184, v179
	v_add_f32_dpp v145, v145, v145 row_mirror row_mask:0xf bank_mask:0xf bound_ctrl:1
	v_fma_f32 v137, -v145, v168, v137
	v_fma_f32 v138, -v145, v169, v138
	v_fma_f32 v139, -v145, v170, v139
	v_fma_f32 v140, -v145, v171, v140
	v_fma_f32 v2, v2, v172, v137
	v_fma_f32 v13, v13, v173, v138
	v_fma_f32 v12, v12, v174, v139
	v_fma_f32 v8, v8, v175, v140
	s_waitcnt lgkmcnt(6)
	v_mul_f32 v137, v206, v198
	v_mul_f32 v138, v206, v199
	v_mul_f32 v145, v2, v186
	v_fma_f32 v145, v13, v187, v145
	v_fma_f32 v145, v12, v188, v145
	v_fma_f32 v145, v8, v189, v145
	ds_read_b128 v[230:233], v5 offset:47616
	ds_read_b128 v[234:237], v5 offset:47872
	ds_read_b128 v[238:241], v5 offset:48128
	ds_read_b128 v[242:245], v5 offset:48384
	ds_read_b128 v[246:249], v5 offset:48640
	ds_read_b32 v250, v9 offset:47616
	v_add_f32_dpp v145, v145, v145 quad_perm:[1,0,3,2] row_mask:0xf bank_mask:0xf bound_ctrl:1
	v_mul_f32 v160, v2, v180
	v_fma_f32 v160, v13, v181, v160
	v_add_f32_dpp v145, v145, v145 quad_perm:[2,3,0,1] row_mask:0xf bank_mask:0xf bound_ctrl:1
	v_fma_f32 v160, v12, v182, v160
	v_fma_f32 v160, v8, v183, v160
	v_add_f32_dpp v145, v145, v145 row_half_mirror row_mask:0xf bank_mask:0xf bound_ctrl:1
	v_mul_f32 v139, v206, v200
	v_mul_f32 v140, v206, v201
	v_add_f32_dpp v145, v145, v145 row_mirror row_mask:0xf bank_mask:0xf bound_ctrl:1
	v_fma_f32 v137, -v145, v190, v137
	v_fma_f32 v138, -v145, v191, v138
	v_fma_f32 v139, -v145, v192, v139
	v_fma_f32 v140, -v145, v193, v140
	v_fma_f32 v2, v2, v194, v137
	v_fma_f32 v13, v13, v195, v138
	v_fma_f32 v12, v12, v196, v139
	v_fma_f32 v8, v8, v197, v140
	s_waitcnt lgkmcnt(6)
	v_mul_f32 v137, v228, v220
	v_mul_f32 v138, v228, v221
	v_mul_f32 v145, v2, v208
	v_fma_f32 v145, v13, v209, v145
	v_fma_f32 v145, v12, v210, v145
	v_fma_f32 v145, v8, v211, v145
	s_nop 1
	v_add_f32_dpp v145, v145, v145 quad_perm:[1,0,3,2] row_mask:0xf bank_mask:0xf bound_ctrl:1
	v_mul_f32 v161, v2, v202
	v_fma_f32 v161, v13, v203, v161
	v_add_f32_dpp v145, v145, v145 quad_perm:[2,3,0,1] row_mask:0xf bank_mask:0xf bound_ctrl:1
	v_fma_f32 v161, v12, v204, v161
	v_fma_f32 v161, v8, v205, v161
	v_add_f32_dpp v145, v145, v145 row_half_mirror row_mask:0xf bank_mask:0xf bound_ctrl:1
	v_mul_f32 v139, v228, v222
	v_mul_f32 v140, v228, v223
	v_add_f32_dpp v145, v145, v145 row_mirror row_mask:0xf bank_mask:0xf bound_ctrl:1
	v_fma_f32 v137, -v145, v212, v137
	v_fma_f32 v138, -v145, v213, v138
	v_fma_f32 v139, -v145, v214, v139
	v_fma_f32 v140, -v145, v215, v140
	v_fma_f32 v2, v2, v216, v137
	v_fma_f32 v13, v13, v217, v138
	v_fma_f32 v12, v12, v218, v139
	v_fma_f32 v8, v8, v219, v140
	s_waitcnt lgkmcnt(0)
	v_mul_f32 v137, v250, v242
	v_mul_f32 v138, v250, v243
	v_mul_f32 v145, v2, v230
	v_fma_f32 v145, v13, v231, v145
	v_fma_f32 v145, v12, v232, v145
	v_fma_f32 v145, v8, v233, v145
	s_nop 1
	v_add_f32_dpp v145, v145, v145 quad_perm:[1,0,3,2] row_mask:0xf bank_mask:0xf bound_ctrl:1
	v_mul_f32 v162, v2, v224
	v_fma_f32 v162, v13, v225, v162
	v_add_f32_dpp v145, v145, v145 quad_perm:[2,3,0,1] row_mask:0xf bank_mask:0xf bound_ctrl:1
	v_fma_f32 v162, v12, v226, v162
	v_fma_f32 v162, v8, v227, v162
	v_add_f32_dpp v145, v145, v145 row_half_mirror row_mask:0xf bank_mask:0xf bound_ctrl:1
	v_mul_f32 v139, v250, v244
	v_mul_f32 v140, v250, v245
	v_add_f32_dpp v145, v145, v145 row_mirror row_mask:0xf bank_mask:0xf bound_ctrl:1
	v_fma_f32 v137, -v145, v234, v137
	v_fma_f32 v138, -v145, v235, v138
	v_fma_f32 v139, -v145, v236, v139
	v_fma_f32 v140, -v145, v237, v140
	v_fma_f32 v2, v2, v238, v137
	v_fma_f32 v13, v13, v239, v138
	v_fma_f32 v12, v12, v240, v139
	v_fma_f32 v8, v8, v241, v140
	v_mul_f32 v163, v2, v246
	v_fma_f32 v163, v13, v247, v163
	v_fma_f32 v163, v12, v248, v163
	v_fma_f32 v163, v8, v249, v163
	s_nop 0
	v_and_b32 v244, 8, v3
	v_cmp_ne_u32 vcc, 0, v244
	v_cndmask_b32 v244, v156, v148, vcc
	v_cndmask_b32 v245, v157, v149, vcc
	v_cndmask_b32 v246, v158, v150, vcc
	v_cndmask_b32 v247, v159, v151, vcc
	v_cndmask_b32 v230, v148, v156, vcc
	v_cndmask_b32 v231, v149, v157, vcc
	v_cndmask_b32 v232, v150, v158, vcc
	v_cndmask_b32 v233, v151, v159, vcc
	v_add_f32_dpp v230, v244, v230 row_mirror row_mask:0xf bank_mask:0xf bound_ctrl:1
	v_add_f32_dpp v231, v245, v231 row_mirror row_mask:0xf bank_mask:0xf bound_ctrl:1
	v_add_f32_dpp v232, v246, v232 row_mirror row_mask:0xf bank_mask:0xf bound_ctrl:1
	v_add_f32_dpp v233, v247, v233 row_mirror row_mask:0xf bank_mask:0xf bound_ctrl:1
	v_cndmask_b32 v244, v160, v152, vcc
	v_cndmask_b32 v245, v161, v153, vcc
	v_cndmask_b32 v246, v162, v154, vcc
	v_cndmask_b32 v247, v163, v155, vcc
	v_cndmask_b32 v234, v152, v160, vcc
	v_cndmask_b32 v235, v153, v161, vcc
	v_cndmask_b32 v236, v154, v162, vcc
	v_cndmask_b32 v237, v155, v163, vcc
	v_add_f32_dpp v234, v244, v234 row_mirror row_mask:0xf bank_mask:0xf bound_ctrl:1
	v_add_f32_dpp v235, v245, v235 row_mirror row_mask:0xf bank_mask:0xf bound_ctrl:1
	v_add_f32_dpp v236, v246, v236 row_mirror row_mask:0xf bank_mask:0xf bound_ctrl:1
	v_add_f32_dpp v237, v247, v237 row_mirror row_mask:0xf bank_mask:0xf bound_ctrl:1
	v_and_b32 v244, 4, v3
	v_cmp_ne_u32 vcc, 0, v244
	v_cndmask_b32 v244, v234, v230, vcc
	v_cndmask_b32 v245, v235, v231, vcc
	v_cndmask_b32 v246, v236, v232, vcc
	v_cndmask_b32 v247, v237, v233, vcc
	v_cndmask_b32 v238, v230, v234, vcc
	v_cndmask_b32 v239, v231, v235, vcc
	v_cndmask_b32 v240, v232, v236, vcc
	v_cndmask_b32 v241, v233, v237, vcc
	v_add_f32_dpp v238, v244, v238 row_half_mirror row_mask:0xf bank_mask:0xf bound_ctrl:1
	v_add_f32_dpp v239, v245, v239 row_half_mirror row_mask:0xf bank_mask:0xf bound_ctrl:1
	v_add_f32_dpp v240, v246, v240 row_half_mirror row_mask:0xf bank_mask:0xf bound_ctrl:1
	v_add_f32_dpp v241, v247, v241 row_half_mirror row_mask:0xf bank_mask:0xf bound_ctrl:1
	v_and_b32 v244, 2, v3
	v_cmp_ne_u32 vcc, 0, v244
	v_cndmask_b32 v244, v240, v238, vcc
	v_cndmask_b32 v245, v241, v239, vcc
	v_cndmask_b32 v242, v238, v240, vcc
	v_cndmask_b32 v243, v239, v241, vcc
	v_add_f32_dpp v242, v244, v242 quad_perm:[2,3,0,1] row_mask:0xf bank_mask:0xf bound_ctrl:1
	v_add_f32_dpp v243, v245, v243 quad_perm:[2,3,0,1] row_mask:0xf bank_mask:0xf bound_ctrl:1
	v_and_b32 v244, 1, v3
	v_cmp_ne_u32 vcc, 0, v244
	v_cndmask_b32 v244, v243, v242, vcc
	v_cndmask_b32 v245, v242, v243, vcc
	s_nop 0
	v_add_f32_dpp v19, v244, v245 quad_perm:[1,0,3,2] row_mask:0xf bank_mask:0xf bound_ctrl:1

; #define SCAN_BAR() asm volatile("s_barrier" ::: "memory")
; __device__ __forceinline__ void scan_unit(const Ctx& C0, const float* scn, int T, int quarter, const float* S0, float* Sout, unsigned char* obase, int mode) {
;     ...
;             if (mode == 0) { *(float*)(obase + (size_t)(k * 32 + q) * UPITCH_B + rl * 4) = osel0; *(float*)(obase + (size_t)(k * 32 + 16 + q) * UPITCH_B + rl * 4) = osel1; }
;             SCAN_BAR();
	v_lshl_add_u64 v[14:15], v[6:7], 0, s[0:1]
	v_add_co_u32_e32 v16, vcc, 0xfc29000, v14
	s_mov_b32 s8, 0xfc7f000
	s_nop 0
	v_addc_co_u32_e32 v17, vcc, 0, v15, vcc
	global_store_dword v[16:17], v18, off offset:768
	v_add_co_u32_e32 v16, vcc, 0xfc54000, v14
	s_add_u32 s0, s0, 0xac000
	s_nop 0
	v_addc_co_u32_e32 v17, vcc, 0, v15, vcc
	global_store_dword v[16:17], v19, off offset:768
	s_barrier
	ds_read_b128 v[164:167], v10 offset:0
	ds_read_b128 v[168:171], v10 offset:256
	ds_read_b128 v[172:175], v10 offset:512
	ds_read_b128 v[176:179], v10 offset:768
	ds_read_b128 v[180:183], v10 offset:1024
	ds_read_b32 v184, v11 offset:0
	ds_read_b128 v[186:189], v10 offset:1536
	ds_read_b128 v[190:193], v10 offset:1792
	ds_read_b128 v[194:197], v10 offset:2048
	ds_read_b128 v[198:201], v10 offset:2304
	ds_read_b128 v[202:205], v10 offset:2560
	ds_read_b32 v206, v11 offset:1536
	s_waitcnt lgkmcnt(0)
	v_mul_f32 v137, v184, v176
	v_mul_f32 v138, v184, v177
	v_mul_f32 v145, v2, v164
	v_fma_f32 v145, v13, v165, v145
	v_fma_f32 v145, v12, v166, v145
	v_fma_f32 v145, v8, v167, v145
	ds_read_b128 v[208:211], v10 offset:3072
	ds_read_b128 v[212:215], v10 offset:3328
	ds_read_b128 v[216:219], v10 offset:3584
	ds_read_b128 v[220:223], v10 offset:3840
	ds_read_b128 v[224:227], v10 offset:4096
	ds_read_b32 v228, v11 offset:3072
	v_add_f32_dpp v145, v145, v145 quad_perm:[1,0,3,2] row_mask:0xf bank_mask:0xf bound_ctrl:1
	s_nop 0
	s_nop 0
	v_add_f32_dpp v145, v145, v145 quad_perm:[2,3,0,1] row_mask:0xf bank_mask:0xf bound_ctrl:1
	s_nop 0
	s_nop 0
	v_add_f32_dpp v145, v145, v145 row_half_mirror row_mask:0xf bank_mask:0xf bound_ctrl:1
	v_mul_f32 v139, v184, v178
	v_mul_f32 v140, v184, v179
	v_add_f32_dpp v145, v145, v145 row_mirror row_mask:0xf bank_mask:0xf bound_ctrl:1
	v_fma_f32 v137, -v145, v168, v137
	v_fma_f32 v138, -v145, v169, v138
	v_fma_f32 v139, -v145, v170, v139
	v_fma_f32 v140, -v145, v171, v140
	v_fma_f32 v2, v2, v172, v137
	v_fma_f32 v13, v13, v173, v138
	v_fma_f32 v12, v12, v174, v139
	v_fma_f32 v8, v8, v175, v140
	s_waitcnt lgkmcnt(6)
	v_mul_f32 v137, v206, v198
	v_mul_f32 v138, v206, v199
	v_mul_f32 v145, v2, v186
	v_fma_f32 v145, v13, v187, v145
	v_fma_f32 v145, v12, v188, v145
	v_fma_f32 v145, v8, v189, v145
	ds_read_b128 v[230:233], v10 offset:4608
	ds_read_b128 v[234:237], v10 offset:4864
	ds_read_b128 v[238:241], v10 offset:5120
	ds_read_b128 v[242:245], v10 offset:5376
	ds_read_b128 v[246:249], v10 offset:5632
	ds_read_b32 v250, v11 offset:4608
	v_add_f32_dpp v145, v145, v145 quad_perm:[1,0,3,2] row_mask:0xf bank_mask:0xf bound_ctrl:1
	v_mul_f32 v148, v2, v180
	v_fma_f32 v148, v13, v181, v148
	v_add_f32_dpp v145, v145, v145 quad_perm:[2,3,0,1] row_mask:0xf bank_mask:0xf bound_ctrl:1
	v_fma_f32 v148, v12, v182, v148
	v_fma_f32 v148, v8, v183, v148
	v_add_f32_dpp v145, v145, v145 row_half_mirror row_mask:0xf bank_mask:0xf bound_ctrl:1
	v_mul_f32 v139, v206, v200
	v_mul_f32 v140, v206, v201
	v_add_f32_dpp v145, v145, v145 row_mirror row_mask:0xf bank_mask:0xf bound_ctrl:1
	v_fma_f32 v137, -v145, v190, v137
	v_fma_f32 v138, -v145, v191, v138
	v_fma_f32 v139, -v145, v192, v139
	v_fma_f32 v140, -v145, v193, v140
	v_fma_f32 v2, v2, v194, v137
	v_fma_f32 v13, v13, v195, v138
	v_fma_f32 v12, v12, v196, v139
	v_fma_f32 v8, v8, v197, v140
	s_waitcnt lgkmcnt(6)
	v_mul_f32 v137, v228, v220
	v_mul_f32 v138, v228, v221
	v_mul_f32 v145, v2, v208
	v_fma_f32 v145, v13, v209, v145
	v_fma_f32 v145, v12, v210, v145
	v_fma_f32 v145, v8, v211, v145
	ds_read_b128 v[164:167], v10 offset:6144
	ds_read_b128 v[168:171], v10 offset:6400
	ds_read_b128 v[172:175], v10 offset:6656
	ds_read_b128 v[176:179], v10 offset:6912
	ds_read_b128 v[180:183], v10 offset:7168
	ds_read_b32 v184, v11 offset:6144
	v_add_f32_dpp v145, v145, v145 quad_perm:[1,0,3,2] row_mask:0xf bank_mask:0xf bound_ctrl:1
	v_mul_f32 v149, v2, v202
	v_fma_f32 v149, v13, v203, v149
	v_add_f32_dpp v145, v145, v145 quad_perm:[2,3,0,1] row_mask:0xf bank_mask:0xf bound_ctrl:1
	v_fma_f32 v149, v12, v204, v149
	v_fma_f32 v149, v8, v205, v149
	v_add_f32_dpp v145, v145, v145 row_half_mirror row_mask:0xf bank_mask:0xf bound_ctrl:1
	v_mul_f32 v139, v228, v222
	v_mul_f32 v140, v228, v223
	v_add_f32_dpp v145, v145, v145 row_mirror row_mask:0xf bank_mask:0xf bound_ctrl:1
	v_fma_f32 v137, -v145, v212, v137
	v_fma_f32 v138, -v145, v213, v138
	v_fma_f32 v139, -v145, v214, v139
	v_fma_f32 v140, -v145, v215, v140
	v_fma_f32 v2, v2, v216, v137
	v_fma_f32 v13, v13, v217, v138
	v_fma_f32 v12, v12, v218, v139
	v_fma_f32 v8, v8, v219, v140
	s_waitcnt lgkmcnt(6)
	v_mul_f32 v137, v250, v242
	v_mul_f32 v138, v250, v243
	v_mul_f32 v145, v2, v230
	v_fma_f32 v145, v13, v231, v145
	v_fma_f32 v145, v12, v232, v145
	v_fma_f32 v145, v8, v233, v145
	ds_read_b128 v[186:189], v10 offset:7680
	ds_read_b128 v[190:193], v10 offset:7936
	ds_read_b128 v[194:197], v10 offset:8192
	ds_read_b128 v[198:201], v10 offset:8448
	ds_read_b128 v[202:205], v10 offset:8704
	ds_read_b32 v206, v11 offset:7680
	v_add_f32_dpp v145, v145, v145 quad_perm:[1,0,3,2] row_mask:0xf bank_mask:0xf bound_ctrl:1
	v_mul_f32 v150, v2, v224
	v_fma_f32 v150, v13, v225, v150
	v_add_f32_dpp v145, v145, v145 quad_perm:[2,3,0,1] row_mask:0xf bank_mask:0xf bound_ctrl:1
	v_fma_f32 v150, v12, v226, v150
	v_fma_f32 v150, v8, v227, v150
	v_add_f32_dpp v145, v145, v145 row_half_mirror row_mask:0xf bank_mask:0xf bound_ctrl:1
	v_mul_f32 v139, v250, v244
	v_mul_f32 v140, v250, v245
	v_add_f32_dpp v145, v145, v145 row_mirror row_mask:0xf bank_mask:0xf bound_ctrl:1
	v_fma_f32 v137, -v145, v234, v137
	v_fma_f32 v138, -v145, v235, v138
	v_fma_f32 v139, -v145, v236, v139
	v_fma_f32 v140, -v145, v237, v140
	v_fma_f32 v2, v2, v238, v137
	v_fma_f32 v13, v13, v239, v138
	v_fma_f32 v12, v12, v240, v139
	v_fma_f32 v8, v8, v241, v140
	s_waitcnt lgkmcnt(6)
	v_mul_f32 v137, v184, v176
	v_mul_f32 v138, v184, v177
	v_mul_f32 v145, v2, v164
	v_fma_f32 v145, v13, v165, v145
	v_fma_f32 v145, v12, v166, v145
	v_fma_f32 v145, v8, v167, v145
	ds_read_b128 v[208:211], v10 offset:9216
	ds_read_b128 v[212:215], v10 offset:9472
	ds_read_b128 v[216:219], v10 offset:9728
	ds_read_b128 v[220:223], v10 offset:9984
	ds_read_b128 v[224:227], v10 offset:10240
	ds_read_b32 v228, v11 offset:9216
	v_add_f32_dpp v145, v145, v145 quad_perm:[1,0,3,2] row_mask:0xf bank_mask:0xf bound_ctrl:1
	v_mul_f32 v151, v2, v246
	v_fma_f32 v151, v13, v247, v151
	v_add_f32_dpp v145, v145, v145 quad_perm:[2,3,0,1] row_mask:0xf bank_mask:0xf bound_ctrl:1
	v_fma_f32 v151, v12, v248, v151
	v_fma_f32 v151, v8, v249, v151
	v_add_f32_dpp v145, v145, v145 row_half_mirror row_mask:0xf bank_mask:0xf bound_ctrl:1
	v_mul_f32 v139, v184, v178
	v_mul_f32 v140, v184, v179
	v_add_f32_dpp v145, v145, v145 row_mirror row_mask:0xf bank_mask:0xf bound_ctrl:1
	v_fma_f32 v137, -v145, v168, v137
	v_fma_f32 v138, -v145, v169, v138
	v_fma_f32 v139, -v145, v170, v139
	v_fma_f32 v140, -v145, v171, v140
	v_fma_f32 v2, v2, v172, v137
	v_fma_f32 v13, v13, v173, v138
	v_fma_f32 v12, v12, v174, v139
	v_fma_f32 v8, v8, v175, v140
	s_waitcnt lgkmcnt(6)
	v_mul_f32 v137, v206, v198
	v_mul_f32 v138, v206, v199
	v_mul_f32 v145, v2, v186
	v_fma_f32 v145, v13, v187, v145
	v_fma_f32 v145, v12, v188, v145
	v_fma_f32 v145, v8, v189, v145
	ds_read_b128 v[230:233], v10 offset:10752
	ds_read_b128 v[234:237], v10 offset:11008
	ds_read_b128 v[238:241], v10 offset:11264
	ds_read_b128 v[242:245], v10 offset:11520
	ds_read_b128 v[246:249], v10 offset:11776
	ds_read_b32 v250, v11 offset:10752
	v_add_f32_dpp v145, v145, v145 quad_perm:[1,0,3,2] row_mask:0xf bank_mask:0xf bound_ctrl:1
	v_mul_f32 v152, v2, v180
	v_fma_f32 v152, v13, v181, v152
	v_add_f32_dpp v145, v145, v145 quad_perm:[2,3,0,1] row_mask:0xf bank_mask:0xf bound_ctrl:1
	v_fma_f32 v152, v12, v182, v152
	v_fma_f32 v152, v8, v183, v152
	v_add_f32_dpp v145, v145, v145 row_half_mirror row_mask:0xf bank_mask:0xf bound_ctrl:1
	v_mul_f32 v139, v206, v200
	v_mul_f32 v140, v206, v201
	v_add_f32_dpp v145, v145, v145 row_mirror row_mask:0xf bank_mask:0xf bound_ctrl:1
	v_fma_f32 v137, -v145, v190, v137
	v_fma_f32 v138, -v145, v191, v138
	v_fma_f32 v139, -v145, v192, v139
	v_fma_f32 v140, -v145, v193, v140
	v_fma_f32 v2, v2, v194, v137
	v_fma_f32 v13, v13, v195, v138
	v_fma_f32 v12, v12, v196, v139
	v_fma_f32 v8, v8, v197, v140
	s_waitcnt lgkmcnt(6)
	v_mul_f32 v137, v228, v220
	v_mul_f32 v138, v228, v221
	v_mul_f32 v145, v2, v208
	v_fma_f32 v145, v13, v209, v145
	v_fma_f32 v145, v12, v210, v145
	v_fma_f32 v145, v8, v211, v145
	ds_read_b128 v[164:167], v10 offset:12288
	ds_read_b128 v[168:171], v10 offset:12544
	ds_read_b128 v[172:175], v10 offset:12800
	ds_read_b128 v[176:179], v10 offset:13056
	ds_read_b128 v[180:183], v10 offset:13312
	ds_read_b32 v184, v11 offset:12288
	v_add_f32_dpp v145, v145, v145 quad_perm:[1,0,3,2] row_mask:0xf bank_mask:0xf bound_ctrl:1
	v_mul_f32 v153, v2, v202
	v_fma_f32 v153, v13, v203, v153
	v_add_f32_dpp v145, v145, v145 quad_perm:[2,3,0,1] row_mask:0xf bank_mask:0xf bound_ctrl:1
	v_fma_f32 v153, v12, v204, v153
	v_fma_f32 v153, v8, v205, v153
	v_add_f32_dpp v145, v145, v145 row_half_mirror row_mask:0xf bank_mask:0xf bound_ctrl:1
	v_mul_f32 v139, v228, v222
	v_mul_f32 v140, v228, v223
	v_add_f32_dpp v145, v145, v145 row_mirror row_mask:0xf bank_mask:0xf bound_ctrl:1
	v_fma_f32 v137, -v145, v212, v137
	v_fma_f32 v138, -v145, v213, v138
	v_fma_f32 v139, -v145, v214, v139
	v_fma_f32 v140, -v145, v215, v140
	v_fma_f32 v2, v2, v216, v137
	v_fma_f32 v13, v13, v217, v138
	v_fma_f32 v12, v12, v218, v139
	v_fma_f32 v8, v8, v219, v140
	s_waitcnt lgkmcnt(6)
	v_mul_f32 v137, v250, v242
	v_mul_f32 v138, v250, v243
	v_mul_f32 v145, v2, v230
	v_fma_f32 v145, v13, v231, v145
	v_fma_f32 v145, v12, v232, v145
	v_fma_f32 v145, v8, v233, v145
	ds_read_b128 v[186:189], v10 offset:13824
	ds_read_b128 v[190:193], v10 offset:14080
	ds_read_b128 v[194:197], v10 offset:14336
	ds_read_b128 v[198:201], v10 offset:14592
	ds_read_b128 v[202:205], v10 offset:14848
	ds_read_b32 v206, v11 offset:13824
	v_add_f32_dpp v145, v145, v145 quad_perm:[1,0,3,2] row_mask:0xf bank_mask:0xf bound_ctrl:1
	v_mul_f32 v154, v2, v224
	v_fma_f32 v154, v13, v225, v154
	v_add_f32_dpp v145, v145, v145 quad_perm:[2,3,0,1] row_mask:0xf bank_mask:0xf bound_ctrl:1
	v_fma_f32 v154, v12, v226, v154
	v_fma_f32 v154, v8, v227, v154
	v_add_f32_dpp v145, v145, v145 row_half_mirror row_mask:0xf bank_mask:0xf bound_ctrl:1
	v_mul_f32 v139, v250, v244
	v_mul_f32 v140, v250, v245
	v_add_f32_dpp v145, v145, v145 row_mirror row_mask:0xf bank_mask:0xf bound_ctrl:1
	v_fma_f32 v137, -v145, v234, v137
	v_fma_f32 v138, -v145, v235, v138
	v_fma_f32 v139, -v145, v236, v139
	v_fma_f32 v140, -v145, v237, v140
	v_fma_f32 v2, v2, v238, v137
	v_fma_f32 v13, v13, v239, v138
	v_fma_f32 v12, v12, v240, v139
	v_fma_f32 v8, v8, v241, v140
	s_waitcnt lgkmcnt(6)
	v_mul_f32 v137, v184, v176
	v_mul_f32 v138, v184, v177
	v_mul_f32 v145, v2, v164
	v_fma_f32 v145, v13, v165, v145
	v_fma_f32 v145, v12, v166, v145
	v_fma_f32 v145, v8, v167, v145
	ds_read_b128 v[208:211], v10 offset:15360
	ds_read_b128 v[212:215], v10 offset:15616
	ds_read_b128 v[216:219], v10 offset:15872
	ds_read_b128 v[220:223], v10 offset:16128
	ds_read_b128 v[224:227], v10 offset:16384
	ds_read_b32 v228, v11 offset:15360
	v_add_f32_dpp v145, v145, v145 quad_perm:[1,0,3,2] row_mask:0xf bank_mask:0xf bound_ctrl:1
	v_mul_f32 v155, v2, v246
	v_fma_f32 v155, v13, v247, v155
	v_add_f32_dpp v145, v145, v145 quad_perm:[2,3,0,1] row_mask:0xf bank_mask:0xf bound_ctrl:1
	v_fma_f32 v155, v12, v248, v155
	v_fma_f32 v155, v8, v249, v155
	v_add_f32_dpp v145, v145, v145 row_half_mirror row_mask:0xf bank_mask:0xf bound_ctrl:1
	v_mul_f32 v139, v184, v178
	v_mul_f32 v140, v184, v179
	v_add_f32_dpp v145, v145, v145 row_mirror row_mask:0xf bank_mask:0xf bound_ctrl:1
	v_fma_f32 v137, -v145, v168, v137
	v_fma_f32 v138, -v145, v169, v138
	v_fma_f32 v139, -v145, v170, v139
	v_fma_f32 v140, -v145, v171, v140
	v_fma_f32 v2, v2, v172, v137
	v_fma_f32 v13, v13, v173, v138
	v_fma_f32 v12, v12, v174, v139
	v_fma_f32 v8, v8, v175, v140
	s_waitcnt lgkmcnt(6)
	v_mul_f32 v137, v206, v198
	v_mul_f32 v138, v206, v199
	v_mul_f32 v145, v2, v186
	v_fma_f32 v145, v13, v187, v145
	v_fma_f32 v145, v12, v188, v145
	v_fma_f32 v145, v8, v189, v145
	ds_read_b128 v[230:233], v10 offset:16896
	ds_read_b128 v[234:237], v10 offset:17152
	ds_read_b128 v[238:241], v10 offset:17408
	ds_read_b128 v[242:245], v10 offset:17664
	ds_read_b128 v[246:249], v10 offset:17920
	ds_read_b32 v250, v11 offset:16896
	v_add_f32_dpp v145, v145, v145 quad_perm:[1,0,3,2] row_mask:0xf bank_mask:0xf bound_ctrl:1
	v_mul_f32 v156, v2, v180
	v_fma_f32 v156, v13, v181, v156
	v_add_f32_dpp v145, v145, v145 quad_perm:[2,3,0,1] row_mask:0xf bank_mask:0xf bound_ctrl:1
	v_fma_f32 v156, v12, v182, v156
	v_fma_f32 v156, v8, v183, v156
	v_add_f32_dpp v145, v145, v145 row_half_mirror row_mask:0xf bank_mask:0xf bound_ctrl:1
	v_mul_f32 v139, v206, v200
	v_mul_f32 v140, v206, v201
	v_add_f32_dpp v145, v145, v145 row_mirror row_mask:0xf bank_mask:0xf bound_ctrl:1
	v_fma_f32 v137, -v145, v190, v137
	v_fma_f32 v138, -v145, v191, v138
	v_fma_f32 v139, -v145, v192, v139
	v_fma_f32 v140, -v145, v193, v140
	v_fma_f32 v2, v2, v194, v137
	v_fma_f32 v13, v13, v195, v138
	v_fma_f32 v12, v12, v196, v139
	v_fma_f32 v8, v8, v197, v140
	s_waitcnt lgkmcnt(6)
	v_mul_f32 v137, v228, v220
	v_mul_f32 v138, v228, v221
	v_mul_f32 v145, v2, v208
	v_fma_f32 v145, v13, v209, v145
	v_fma_f32 v145, v12, v210, v145
	v_fma_f32 v145, v8, v211, v145
	ds_read_b128 v[164:167], v10 offset:18432
	ds_read_b128 v[168:171], v10 offset:18688
	ds_read_b128 v[172:175], v10 offset:18944
	ds_read_b128 v[176:179], v10 offset:19200
	ds_read_b128 v[180:183], v10 offset:19456
	ds_read_b32 v184, v11 offset:18432
	v_add_f32_dpp v145, v145, v145 quad_perm:[1,0,3,2] row_mask:0xf bank_mask:0xf bound_ctrl:1
	v_mul_f32 v157, v2, v202
	v_fma_f32 v157, v13, v203, v157
	v_add_f32_dpp v145, v145, v145 quad_perm:[2,3,0,1] row_mask:0xf bank_mask:0xf bound_ctrl:1
	v_fma_f32 v157, v12, v204, v157
	v_fma_f32 v157, v8, v205, v157
	v_add_f32_dpp v145, v145, v145 row_half_mirror row_mask:0xf bank_mask:0xf bound_ctrl:1
	v_mul_f32 v139, v228, v222
	v_mul_f32 v140, v228, v223
	v_add_f32_dpp v145, v145, v145 row_mirror row_mask:0xf bank_mask:0xf bound_ctrl:1
	v_fma_f32 v137, -v145, v212, v137
	v_fma_f32 v138, -v145, v213, v138
	v_fma_f32 v139, -v145, v214, v139
	v_fma_f32 v140, -v145, v215, v140
	v_fma_f32 v2, v2, v216, v137
	v_fma_f32 v13, v13, v217, v138
	v_fma_f32 v12, v12, v218, v139
	v_fma_f32 v8, v8, v219, v140
	s_waitcnt lgkmcnt(6)
	v_mul_f32 v137, v250, v242
	v_mul_f32 v138, v250, v243
	v_mul_f32 v145, v2, v230
	v_fma_f32 v145, v13, v231, v145
	v_fma_f32 v145, v12, v232, v145
	v_fma_f32 v145, v8, v233, v145
	ds_read_b128 v[186:189], v10 offset:19968
	ds_read_b128 v[190:193], v10 offset:20224
	ds_read_b128 v[194:197], v10 offset:20480
	ds_read_b128 v[198:201], v10 offset:20736
	ds_read_b128 v[202:205], v10 offset:20992
	ds_read_b32 v206, v11 offset:19968
	v_add_f32_dpp v145, v145, v145 quad_perm:[1,0,3,2] row_mask:0xf bank_mask:0xf bound_ctrl:1
	v_mul_f32 v158, v2, v224
	v_fma_f32 v158, v13, v225, v158
	v_add_f32_dpp v145, v145, v145 quad_perm:[2,3,0,1] row_mask:0xf bank_mask:0xf bound_ctrl:1
	v_fma_f32 v158, v12, v226, v158
	v_fma_f32 v158, v8, v227, v158
	v_add_f32_dpp v145, v145, v145 row_half_mirror row_mask:0xf bank_mask:0xf bound_ctrl:1
	v_mul_f32 v139, v250, v244
	v_mul_f32 v140, v250, v245
	v_add_f32_dpp v145, v145, v145 row_mirror row_mask:0xf bank_mask:0xf bound_ctrl:1
	v_fma_f32 v137, -v145, v234, v137
	v_fma_f32 v138, -v145, v235, v138
	v_fma_f32 v139, -v145, v236, v139
	v_fma_f32 v140, -v145, v237, v140
	v_fma_f32 v2, v2, v238, v137
	v_fma_f32 v13, v13, v239, v138
	v_fma_f32 v12, v12, v240, v139
	v_fma_f32 v8, v8, v241, v140
	s_waitcnt lgkmcnt(6)
	v_mul_f32 v137, v184, v176
	v_mul_f32 v138, v184, v177
	v_mul_f32 v145, v2, v164
	v_fma_f32 v145, v13, v165, v145
	v_fma_f32 v145, v12, v166, v145
	v_fma_f32 v145, v8, v167, v145
	ds_read_b128 v[208:211], v10 offset:21504
	ds_read_b128 v[212:215], v10 offset:21760
	ds_read_b128 v[216:219], v10 offset:22016
	ds_read_b128 v[220:223], v10 offset:22272
	ds_read_b128 v[224:227], v10 offset:22528
	ds_read_b32 v228, v11 offset:21504
	v_add_f32_dpp v145, v145, v145 quad_perm:[1,0,3,2] row_mask:0xf bank_mask:0xf bound_ctrl:1
	v_mul_f32 v159, v2, v246
	v_fma_f32 v159, v13, v247, v159
	v_add_f32_dpp v145, v145, v145 quad_perm:[2,3,0,1] row_mask:0xf bank_mask:0xf bound_ctrl:1
	v_fma_f32 v159, v12, v248, v159
	v_fma_f32 v159, v8, v249, v159
	v_add_f32_dpp v145, v145, v145 row_half_mirror row_mask:0xf bank_mask:0xf bound_ctrl:1
	v_mul_f32 v139, v184, v178
	v_mul_f32 v140, v184, v179
	v_add_f32_dpp v145, v145, v145 row_mirror row_mask:0xf bank_mask:0xf bound_ctrl:1
	v_fma_f32 v137, -v145, v168, v137
	v_fma_f32 v138, -v145, v169, v138
	v_fma_f32 v139, -v145, v170, v139
	v_fma_f32 v140, -v145, v171, v140
	v_fma_f32 v2, v2, v172, v137
	v_fma_f32 v13, v13, v173, v138
	v_fma_f32 v12, v12, v174, v139
	v_fma_f32 v8, v8, v175, v140
	s_waitcnt lgkmcnt(6)
	v_mul_f32 v137, v206, v198
	v_mul_f32 v138, v206, v199
	v_mul_f32 v145, v2, v186
	v_fma_f32 v145, v13, v187, v145
	v_fma_f32 v145, v12, v188, v145
	v_fma_f32 v145, v8, v189, v145
	ds_read_b128 v[230:233], v10 offset:23040
	ds_read_b128 v[234:237], v10 offset:23296
	ds_read_b128 v[238:241], v10 offset:23552
	ds_read_b128 v[242:245], v10 offset:23808
	ds_read_b128 v[246:249], v10 offset:24064
	ds_read_b32 v250, v11 offset:23040
	v_add_f32_dpp v145, v145, v145 quad_perm:[1,0,3,2] row_mask:0xf bank_mask:0xf bound_ctrl:1
	v_mul_f32 v160, v2, v180
	v_fma_f32 v160, v13, v181, v160
	v_add_f32_dpp v145, v145, v145 quad_perm:[2,3,0,1] row_mask:0xf bank_mask:0xf bound_ctrl:1
	v_fma_f32 v160, v12, v182, v160
	v_fma_f32 v160, v8, v183, v160
	v_add_f32_dpp v145, v145, v145 row_half_mirror row_mask:0xf bank_mask:0xf bound_ctrl:1
	v_mul_f32 v139, v206, v200
	v_mul_f32 v140, v206, v201
	v_add_f32_dpp v145, v145, v145 row_mirror row_mask:0xf bank_mask:0xf bound_ctrl:1
	v_fma_f32 v137, -v145, v190, v137
	v_fma_f32 v138, -v145, v191, v138
	v_fma_f32 v139, -v145, v192, v139
	v_fma_f32 v140, -v145, v193, v140
	v_fma_f32 v2, v2, v194, v137
	v_fma_f32 v13, v13, v195, v138
	v_fma_f32 v12, v12, v196, v139
	v_fma_f32 v8, v8, v197, v140
	s_waitcnt lgkmcnt(6)
	v_mul_f32 v137, v228, v220
	v_mul_f32 v138, v228, v221
	v_mul_f32 v145, v2, v208
	v_fma_f32 v145, v13, v209, v145
	v_fma_f32 v145, v12, v210, v145
	v_fma_f32 v145, v8, v211, v145
	ds_read_b128 v[164:167], v10 offset:24576
	ds_read_b128 v[168:171], v10 offset:24832
	ds_read_b128 v[172:175], v10 offset:25088
	ds_read_b128 v[176:179], v10 offset:25344
	ds_read_b128 v[180:183], v10 offset:25600
	ds_read_b32 v184, v11 offset:24576
	v_add_f32_dpp v145, v145, v145 quad_perm:[1,0,3,2] row_mask:0xf bank_mask:0xf bound_ctrl:1
	v_mul_f32 v161, v2, v202
	v_fma_f32 v161, v13, v203, v161
	v_add_f32_dpp v145, v145, v145 quad_perm:[2,3,0,1] row_mask:0xf bank_mask:0xf bound_ctrl:1
	v_fma_f32 v161, v12, v204, v161
	v_fma_f32 v161, v8, v205, v161
	v_add_f32_dpp v145, v145, v145 row_half_mirror row_mask:0xf bank_mask:0xf bound_ctrl:1
	v_mul_f32 v139, v228, v222
	v_mul_f32 v140, v228, v223
	v_add_f32_dpp v145, v145, v145 row_mirror row_mask:0xf bank_mask:0xf bound_ctrl:1
	v_fma_f32 v137, -v145, v212, v137
	v_fma_f32 v138, -v145, v213, v138
	v_fma_f32 v139, -v145, v214, v139
	v_fma_f32 v140, -v145, v215, v140
	v_fma_f32 v2, v2, v216, v137
	v_fma_f32 v13, v13, v217, v138
	v_fma_f32 v12, v12, v218, v139
	v_fma_f32 v8, v8, v219, v140
	s_waitcnt lgkmcnt(6)
	v_mul_f32 v137, v250, v242
	v_mul_f32 v138, v250, v243
	v_mul_f32 v145, v2, v230
	v_fma_f32 v145, v13, v231, v145
	v_fma_f32 v145, v12, v232, v145
	v_fma_f32 v145, v8, v233, v145
	ds_read_b128 v[186:189], v10 offset:26112
	ds_read_b128 v[190:193], v10 offset:26368
	ds_read_b128 v[194:197], v10 offset:26624
	ds_read_b128 v[198:201], v10 offset:26880
	ds_read_b128 v[202:205], v10 offset:27136
	ds_read_b32 v206, v11 offset:26112
	v_add_f32_dpp v145, v145, v145 quad_perm:[1,0,3,2] row_mask:0xf bank_mask:0xf bound_ctrl:1
	v_mul_f32 v162, v2, v224
	v_fma_f32 v162, v13, v225, v162
	v_add_f32_dpp v145, v145, v145 quad_perm:[2,3,0,1] row_mask:0xf bank_mask:0xf bound_ctrl:1
	v_fma_f32 v162, v12, v226, v162
	v_fma_f32 v162, v8, v227, v162
	v_add_f32_dpp v145, v145, v145 row_half_mirror row_mask:0xf bank_mask:0xf bound_ctrl:1
	v_mul_f32 v139, v250, v244
	v_mul_f32 v140, v250, v245
	v_add_f32_dpp v145, v145, v145 row_mirror row_mask:0xf bank_mask:0xf bound_ctrl:1
	v_fma_f32 v137, -v145, v234, v137
	v_fma_f32 v138, -v145, v235, v138
	v_fma_f32 v139, -v145, v236, v139
	v_fma_f32 v140, -v145, v237, v140
	v_fma_f32 v2, v2, v238, v137
	v_fma_f32 v13, v13, v239, v138
	v_fma_f32 v12, v12, v240, v139
	v_fma_f32 v8, v8, v241, v140
	s_waitcnt lgkmcnt(6)
	v_mul_f32 v137, v184, v176
	v_mul_f32 v138, v184, v177
	v_mul_f32 v145, v2, v164
	v_fma_f32 v145, v13, v165, v145
	v_fma_f32 v145, v12, v166, v145
	v_fma_f32 v145, v8, v167, v145
	ds_read_b128 v[208:211], v10 offset:27648
	ds_read_b128 v[212:215], v10 offset:27904
	ds_read_b128 v[216:219], v10 offset:28160
	ds_read_b128 v[220:223], v10 offset:28416
	ds_read_b128 v[224:227], v10 offset:28672
	ds_read_b32 v228, v11 offset:27648
	v_add_f32_dpp v145, v145, v145 quad_perm:[1,0,3,2] row_mask:0xf bank_mask:0xf bound_ctrl:1
	v_mul_f32 v163, v2, v246
	v_fma_f32 v163, v13, v247, v163
	v_add_f32_dpp v145, v145, v145 quad_perm:[2,3,0,1] row_mask:0xf bank_mask:0xf bound_ctrl:1
	v_fma_f32 v163, v12, v248, v163
	v_fma_f32 v163, v8, v249, v163
	v_add_f32_dpp v145, v145, v145 row_half_mirror row_mask:0xf bank_mask:0xf bound_ctrl:1
	v_mul_f32 v139, v184, v178
	v_mul_f32 v140, v184, v179
	v_add_f32_dpp v145, v145, v145 row_mirror row_mask:0xf bank_mask:0xf bound_ctrl:1
	v_fma_f32 v137, -v145, v168, v137
	v_fma_f32 v138, -v145, v169, v138
	v_fma_f32 v139, -v145, v170, v139
	v_fma_f32 v140, -v145, v171, v140
	v_fma_f32 v2, v2, v172, v137
	v_fma_f32 v13, v13, v173, v138
	v_fma_f32 v12, v12, v174, v139
	v_fma_f32 v8, v8, v175, v140
	s_waitcnt lgkmcnt(6)
	v_mul_f32 v137, v206, v198
	v_mul_f32 v138, v206, v199
	v_mul_f32 v145, v2, v186
	v_fma_f32 v145, v13, v187, v145
	v_fma_f32 v145, v12, v188, v145
	v_fma_f32 v145, v8, v189, v145
	v_and_b32 v244, 8, v3
	v_cmp_ne_u32 vcc, 0, v244
	v_cndmask_b32 v244, v156, v148, vcc
	v_cndmask_b32 v245, v157, v149, vcc
	v_cndmask_b32 v246, v158, v150, vcc
	v_cndmask_b32 v247, v159, v151, vcc
	v_cndmask_b32 v230, v148, v156, vcc
	v_cndmask_b32 v231, v149, v157, vcc
	v_cndmask_b32 v232, v150, v158, vcc
	v_cndmask_b32 v233, v151, v159, vcc
	v_add_f32_dpp v230, v244, v230 row_mirror row_mask:0xf bank_mask:0xf bound_ctrl:1
	v_add_f32_dpp v231, v245, v231 row_mirror row_mask:0xf bank_mask:0xf bound_ctrl:1
	v_add_f32_dpp v232, v246, v232 row_mirror row_mask:0xf bank_mask:0xf bound_ctrl:1
	v_add_f32_dpp v233, v247, v233 row_mirror row_mask:0xf bank_mask:0xf bound_ctrl:1
	v_cndmask_b32 v244, v160, v152, vcc
	v_cndmask_b32 v245, v161, v153, vcc
	v_cndmask_b32 v246, v162, v154, vcc
	v_cndmask_b32 v247, v163, v155, vcc
	v_cndmask_b32 v234, v152, v160, vcc
	v_cndmask_b32 v235, v153, v161, vcc
	v_cndmask_b32 v236, v154, v162, vcc
	v_cndmask_b32 v237, v155, v163, vcc
	v_add_f32_dpp v234, v244, v234 row_mirror row_mask:0xf bank_mask:0xf bound_ctrl:1
	v_add_f32_dpp v235, v245, v235 row_mirror row_mask:0xf bank_mask:0xf bound_ctrl:1
	v_add_f32_dpp v236, v246, v236 row_mirror row_mask:0xf bank_mask:0xf bound_ctrl:1
	v_add_f32_dpp v237, v247, v237 row_mirror row_mask:0xf bank_mask:0xf bound_ctrl:1
	v_and_b32 v244, 4, v3
	v_cmp_ne_u32 vcc, 0, v244
	v_cndmask_b32 v244, v234, v230, vcc
	v_cndmask_b32 v245, v235, v231, vcc
	v_cndmask_b32 v246, v236, v232, vcc
	v_cndmask_b32 v247, v237, v233, vcc
	v_cndmask_b32 v238, v230, v234, vcc
	v_cndmask_b32 v239, v231, v235, vcc
	v_cndmask_b32 v240, v232, v236, vcc
	v_cndmask_b32 v241, v233, v237, vcc
	v_add_f32_dpp v238, v244, v238 row_half_mirror row_mask:0xf bank_mask:0xf bound_ctrl:1
	v_add_f32_dpp v239, v245, v239 row_half_mirror row_mask:0xf bank_mask:0xf bound_ctrl:1
	v_add_f32_dpp v240, v246, v240 row_half_mirror row_mask:0xf bank_mask:0xf bound_ctrl:1
	v_add_f32_dpp v241, v247, v241 row_half_mirror row_mask:0xf bank_mask:0xf bound_ctrl:1
	v_and_b32 v244, 2, v3
	v_cmp_ne_u32 vcc, 0, v244
	v_cndmask_b32 v244, v240, v238, vcc
	v_cndmask_b32 v245, v241, v239, vcc
	v_cndmask_b32 v242, v238, v240, vcc
	v_cndmask_b32 v243, v239, v241, vcc
	v_add_f32_dpp v242, v244, v242 quad_perm:[2,3,0,1] row_mask:0xf bank_mask:0xf bound_ctrl:1
	v_add_f32_dpp v243, v245, v243 quad_perm:[2,3,0,1] row_mask:0xf bank_mask:0xf bound_ctrl:1
	v_and_b32 v244, 1, v3
	v_cmp_ne_u32 vcc, 0, v244
	v_cndmask_b32 v244, v243, v242, vcc
	v_cndmask_b32 v245, v242, v243, vcc
	s_nop 0
	v_add_f32_dpp v18, v244, v245 quad_perm:[1,0,3,2] row_mask:0xf bank_mask:0xf bound_ctrl:1
	ds_read_b128 v[230:233], v10 offset:29184
	ds_read_b128 v[234:237], v10 offset:29440
	ds_read_b128 v[238:241], v10 offset:29696
	ds_read_b128 v[242:245], v10 offset:29952
	ds_read_b128 v[246:249], v10 offset:30208
	ds_read_b32 v250, v11 offset:29184
	v_add_f32_dpp v145, v145, v145 quad_perm:[1,0,3,2] row_mask:0xf bank_mask:0xf bound_ctrl:1
	v_mul_f32 v148, v2, v180
	v_fma_f32 v148, v13, v181, v148
	v_add_f32_dpp v145, v145, v145 quad_perm:[2,3,0,1] row_mask:0xf bank_mask:0xf bound_ctrl:1
	v_fma_f32 v148, v12, v182, v148
	v_fma_f32 v148, v8, v183, v148
	v_add_f32_dpp v145, v145, v145 row_half_mirror row_mask:0xf bank_mask:0xf bound_ctrl:1
	v_mul_f32 v139, v206, v200
	v_mul_f32 v140, v206, v201
	v_add_f32_dpp v145, v145, v145 row_mirror row_mask:0xf bank_mask:0xf bound_ctrl:1
	v_fma_f32 v137, -v145, v190, v137
	v_fma_f32 v138, -v145, v191, v138
	v_fma_f32 v139, -v145, v192, v139
	v_fma_f32 v140, -v145, v193, v140
	v_fma_f32 v2, v2, v194, v137
	v_fma_f32 v13, v13, v195, v138
	v_fma_f32 v12, v12, v196, v139
	v_fma_f32 v8, v8, v197, v140
	s_waitcnt lgkmcnt(6)
	v_mul_f32 v137, v228, v220
	v_mul_f32 v138, v228, v221
	v_mul_f32 v145, v2, v208
	v_fma_f32 v145, v13, v209, v145
	v_fma_f32 v145, v12, v210, v145
	v_fma_f32 v145, v8, v211, v145
	ds_read_b128 v[164:167], v10 offset:30720
	ds_read_b128 v[168:171], v10 offset:30976
	ds_read_b128 v[172:175], v10 offset:31232
	ds_read_b128 v[176:179], v10 offset:31488
	ds_read_b128 v[180:183], v10 offset:31744
	ds_read_b32 v184, v11 offset:30720
	v_add_f32_dpp v145, v145, v145 quad_perm:[1,0,3,2] row_mask:0xf bank_mask:0xf bound_ctrl:1
	v_mul_f32 v149, v2, v202
	v_fma_f32 v149, v13, v203, v149
	v_add_f32_dpp v145, v145, v145 quad_perm:[2,3,0,1] row_mask:0xf bank_mask:0xf bound_ctrl:1
	v_fma_f32 v149, v12, v204, v149
	v_fma_f32 v149, v8, v205, v149
	v_add_f32_dpp v145, v145, v145 row_half_mirror row_mask:0xf bank_mask:0xf bound_ctrl:1
	v_mul_f32 v139, v228, v222
	v_mul_f32 v140, v228, v223
	v_add_f32_dpp v145, v145, v145 row_mirror row_mask:0xf bank_mask:0xf bound_ctrl:1
	v_fma_f32 v137, -v145, v212, v137
	v_fma_f32 v138, -v145, v213, v138
	v_fma_f32 v139, -v145, v214, v139
	v_fma_f32 v140, -v145, v215, v140
	v_fma_f32 v2, v2, v216, v137
	v_fma_f32 v13, v13, v217, v138
	v_fma_f32 v12, v12, v218, v139
	v_fma_f32 v8, v8, v219, v140
	s_waitcnt lgkmcnt(6)
	v_mul_f32 v137, v250, v242
	v_mul_f32 v138, v250, v243
	v_mul_f32 v145, v2, v230
	v_fma_f32 v145, v13, v231, v145
	v_fma_f32 v145, v12, v232, v145
	v_fma_f32 v145, v8, v233, v145
	ds_read_b128 v[186:189], v10 offset:32256
	ds_read_b128 v[190:193], v10 offset:32512
	ds_read_b128 v[194:197], v10 offset:32768
	ds_read_b128 v[198:201], v10 offset:33024
	ds_read_b128 v[202:205], v10 offset:33280
	ds_read_b32 v206, v11 offset:32256
	v_add_f32_dpp v145, v145, v145 quad_perm:[1,0,3,2] row_mask:0xf bank_mask:0xf bound_ctrl:1
	v_mul_f32 v150, v2, v224
	v_fma_f32 v150, v13, v225, v150
	v_add_f32_dpp v145, v145, v145 quad_perm:[2,3,0,1] row_mask:0xf bank_mask:0xf bound_ctrl:1
	v_fma_f32 v150, v12, v226, v150
	v_fma_f32 v150, v8, v227, v150
	v_add_f32_dpp v145, v145, v145 row_half_mirror row_mask:0xf bank_mask:0xf bound_ctrl:1
	v_mul_f32 v139, v250, v244
	v_mul_f32 v140, v250, v245
	v_add_f32_dpp v145, v145, v145 row_mirror row_mask:0xf bank_mask:0xf bound_ctrl:1
	v_fma_f32 v137, -v145, v234, v137
	v_fma_f32 v138, -v145, v235, v138
	v_fma_f32 v139, -v145, v236, v139
	v_fma_f32 v140, -v145, v237, v140
	v_fma_f32 v2, v2, v238, v137
	v_fma_f32 v13, v13, v239, v138
	v_fma_f32 v12, v12, v240, v139
	v_fma_f32 v8, v8, v241, v140
	s_waitcnt lgkmcnt(6)
	v_mul_f32 v137, v184, v176
	v_mul_f32 v138, v184, v177
	v_mul_f32 v145, v2, v164
	v_fma_f32 v145, v13, v165, v145
	v_fma_f32 v145, v12, v166, v145
	v_fma_f32 v145, v8, v167, v145
	ds_read_b128 v[208:211], v10 offset:33792
	ds_read_b128 v[212:215], v10 offset:34048
	ds_read_b128 v[216:219], v10 offset:34304
	ds_read_b128 v[220:223], v10 offset:34560
	ds_read_b128 v[224:227], v10 offset:34816
	ds_read_b32 v228, v11 offset:33792
	v_add_f32_dpp v145, v145, v145 quad_perm:[1,0,3,2] row_mask:0xf bank_mask:0xf bound_ctrl:1
	v_mul_f32 v151, v2, v246
	v_fma_f32 v151, v13, v247, v151
	v_add_f32_dpp v145, v145, v145 quad_perm:[2,3,0,1] row_mask:0xf bank_mask:0xf bound_ctrl:1
	v_fma_f32 v151, v12, v248, v151
	v_fma_f32 v151, v8, v249, v151
	v_add_f32_dpp v145, v145, v145 row_half_mirror row_mask:0xf bank_mask:0xf bound_ctrl:1
	v_mul_f32 v139, v184, v178
	v_mul_f32 v140, v184, v179
	v_add_f32_dpp v145, v145, v145 row_mirror row_mask:0xf bank_mask:0xf bound_ctrl:1
	v_fma_f32 v137, -v145, v168, v137
	v_fma_f32 v138, -v145, v169, v138
	v_fma_f32 v139, -v145, v170, v139
	v_fma_f32 v140, -v145, v171, v140
	v_fma_f32 v2, v2, v172, v137
	v_fma_f32 v13, v13, v173, v138
	v_fma_f32 v12, v12, v174, v139
	v_fma_f32 v8, v8, v175, v140
	s_waitcnt lgkmcnt(6)
	v_mul_f32 v137, v206, v198
	v_mul_f32 v138, v206, v199
	v_mul_f32 v145, v2, v186
	v_fma_f32 v145, v13, v187, v145
	v_fma_f32 v145, v12, v188, v145
	v_fma_f32 v145, v8, v189, v145
	ds_read_b128 v[230:233], v10 offset:35328
	ds_read_b128 v[234:237], v10 offset:35584
	ds_read_b128 v[238:241], v10 offset:35840
	ds_read_b128 v[242:245], v10 offset:36096
	ds_read_b128 v[246:249], v10 offset:36352
	ds_read_b32 v250, v11 offset:35328
	v_add_f32_dpp v145, v145, v145 quad_perm:[1,0,3,2] row_mask:0xf bank_mask:0xf bound_ctrl:1
	v_mul_f32 v152, v2, v180
	v_fma_f32 v152, v13, v181, v152
	v_add_f32_dpp v145, v145, v145 quad_perm:[2,3,0,1] row_mask:0xf bank_mask:0xf bound_ctrl:1
	v_fma_f32 v152, v12, v182, v152
	v_fma_f32 v152, v8, v183, v152
	v_add_f32_dpp v145, v145, v145 row_half_mirror row_mask:0xf bank_mask:0xf bound_ctrl:1
	v_mul_f32 v139, v206, v200
	v_mul_f32 v140, v206, v201
	v_add_f32_dpp v145, v145, v145 row_mirror row_mask:0xf bank_mask:0xf bound_ctrl:1
	v_fma_f32 v137, -v145, v190, v137
	v_fma_f32 v138, -v145, v191, v138
	v_fma_f32 v139, -v145, v192, v139
	v_fma_f32 v140, -v145, v193, v140
	v_fma_f32 v2, v2, v194, v137
	v_fma_f32 v13, v13, v195, v138
	v_fma_f32 v12, v12, v196, v139
	v_fma_f32 v8, v8, v197, v140
	s_waitcnt lgkmcnt(6)
	v_mul_f32 v137, v228, v220
	v_mul_f32 v138, v228, v221
	v_mul_f32 v145, v2, v208
	v_fma_f32 v145, v13, v209, v145
	v_fma_f32 v145, v12, v210, v145
	v_fma_f32 v145, v8, v211, v145
	ds_read_b128 v[164:167], v10 offset:36864
	ds_read_b128 v[168:171], v10 offset:37120
	ds_read_b128 v[172:175], v10 offset:37376
	ds_read_b128 v[176:179], v10 offset:37632
	ds_read_b128 v[180:183], v10 offset:37888
	ds_read_b32 v184, v11 offset:36864
	v_add_f32_dpp v145, v145, v145 quad_perm:[1,0,3,2] row_mask:0xf bank_mask:0xf bound_ctrl:1
	v_mul_f32 v153, v2, v202
	v_fma_f32 v153, v13, v203, v153
	v_add_f32_dpp v145, v145, v145 quad_perm:[2,3,0,1] row_mask:0xf bank_mask:0xf bound_ctrl:1
	v_fma_f32 v153, v12, v204, v153
	v_fma_f32 v153, v8, v205, v153
	v_add_f32_dpp v145, v145, v145 row_half_mirror row_mask:0xf bank_mask:0xf bound_ctrl:1
	v_mul_f32 v139, v228, v222
	v_mul_f32 v140, v228, v223
	v_add_f32_dpp v145, v145, v145 row_mirror row_mask:0xf bank_mask:0xf bound_ctrl:1
	v_fma_f32 v137, -v145, v212, v137
	v_fma_f32 v138, -v145, v213, v138
	v_fma_f32 v139, -v145, v214, v139
	v_fma_f32 v140, -v145, v215, v140
	v_fma_f32 v2, v2, v216, v137
	v_fma_f32 v13, v13, v217, v138
	v_fma_f32 v12, v12, v218, v139
	v_fma_f32 v8, v8, v219, v140
	s_waitcnt lgkmcnt(6)
	v_mul_f32 v137, v250, v242
	v_mul_f32 v138, v250, v243
	v_mul_f32 v145, v2, v230
	v_fma_f32 v145, v13, v231, v145
	v_fma_f32 v145, v12, v232, v145
	v_fma_f32 v145, v8, v233, v145
	ds_read_b128 v[186:189], v10 offset:38400
	ds_read_b128 v[190:193], v10 offset:38656
	ds_read_b128 v[194:197], v10 offset:38912
	ds_read_b128 v[198:201], v10 offset:39168
	ds_read_b128 v[202:205], v10 offset:39424
	ds_read_b32 v206, v11 offset:38400
	v_add_f32_dpp v145, v145, v145 quad_perm:[1,0,3,2] row_mask:0xf bank_mask:0xf bound_ctrl:1
	v_mul_f32 v154, v2, v224
	v_fma_f32 v154, v13, v225, v154
	v_add_f32_dpp v145, v145, v145 quad_perm:[2,3,0,1] row_mask:0xf bank_mask:0xf bound_ctrl:1
	v_fma_f32 v154, v12, v226, v154
	v_fma_f32 v154, v8, v227, v154
	v_add_f32_dpp v145, v145, v145 row_half_mirror row_mask:0xf bank_mask:0xf bound_ctrl:1
	v_mul_f32 v139, v250, v244
	v_mul_f32 v140, v250, v245
	v_add_f32_dpp v145, v145, v145 row_mirror row_mask:0xf bank_mask:0xf bound_ctrl:1
	v_fma_f32 v137, -v145, v234, v137
	v_fma_f32 v138, -v145, v235, v138
	v_fma_f32 v139, -v145, v236, v139
	v_fma_f32 v140, -v145, v237, v140
	v_fma_f32 v2, v2, v238, v137
	v_fma_f32 v13, v13, v239, v138
	v_fma_f32 v12, v12, v240, v139
	v_fma_f32 v8, v8, v241, v140
	s_waitcnt lgkmcnt(6)
	v_mul_f32 v137, v184, v176
	v_mul_f32 v138, v184, v177
	v_mul_f32 v145, v2, v164
	v_fma_f32 v145, v13, v165, v145
	v_fma_f32 v145, v12, v166, v145
	v_fma_f32 v145, v8, v167, v145
	ds_read_b128 v[208:211], v10 offset:39936
	ds_read_b128 v[212:215], v10 offset:40192
	ds_read_b128 v[216:219], v10 offset:40448
	ds_read_b128 v[220:223], v10 offset:40704
	ds_read_b128 v[224:227], v10 offset:40960
	ds_read_b32 v228, v11 offset:39936
	v_add_f32_dpp v145, v145, v145 quad_perm:[1,0,3,2] row_mask:0xf bank_mask:0xf bound_ctrl:1
	v_mul_f32 v155, v2, v246
	v_fma_f32 v155, v13, v247, v155
	v_add_f32_dpp v145, v145, v145 quad_perm:[2,3,0,1] row_mask:0xf bank_mask:0xf bound_ctrl:1
	v_fma_f32 v155, v12, v248, v155
	v_fma_f32 v155, v8, v249, v155
	v_add_f32_dpp v145, v145, v145 row_half_mirror row_mask:0xf bank_mask:0xf bound_ctrl:1
	v_mul_f32 v139, v184, v178
	v_mul_f32 v140, v184, v179
	v_add_f32_dpp v145, v145, v145 row_mirror row_mask:0xf bank_mask:0xf bound_ctrl:1
	v_fma_f32 v137, -v145, v168, v137
	v_fma_f32 v138, -v145, v169, v138
	v_fma_f32 v139, -v145, v170, v139
	v_fma_f32 v140, -v145, v171, v140
	v_fma_f32 v2, v2, v172, v137
	v_fma_f32 v13, v13, v173, v138
	v_fma_f32 v12, v12, v174, v139
	v_fma_f32 v8, v8, v175, v140
	s_waitcnt lgkmcnt(6)
	v_mul_f32 v137, v206, v198
	v_mul_f32 v138, v206, v199
	v_mul_f32 v145, v2, v186
	v_fma_f32 v145, v13, v187, v145
	v_fma_f32 v145, v12, v188, v145
	v_fma_f32 v145, v8, v189, v145
	ds_read_b128 v[230:233], v10 offset:41472
	ds_read_b128 v[234:237], v10 offset:41728
	ds_read_b128 v[238:241], v10 offset:41984
	ds_read_b128 v[242:245], v10 offset:42240
	ds_read_b128 v[246:249], v10 offset:42496
	ds_read_b32 v250, v11 offset:41472
	v_add_f32_dpp v145, v145, v145 quad_perm:[1,0,3,2] row_mask:0xf bank_mask:0xf bound_ctrl:1
	v_mul_f32 v156, v2, v180
	v_fma_f32 v156, v13, v181, v156
	v_add_f32_dpp v145, v145, v145 quad_perm:[2,3,0,1] row_mask:0xf bank_mask:0xf bound_ctrl:1
	v_fma_f32 v156, v12, v182, v156
	v_fma_f32 v156, v8, v183, v156
	v_add_f32_dpp v145, v145, v145 row_half_mirror row_mask:0xf bank_mask:0xf bound_ctrl:1
	v_mul_f32 v139, v206, v200
	v_mul_f32 v140, v206, v201
	v_add_f32_dpp v145, v145, v145 row_mirror row_mask:0xf bank_mask:0xf bound_ctrl:1
	v_fma_f32 v137, -v145, v190, v137
	v_fma_f32 v138, -v145, v191, v138
	v_fma_f32 v139, -v145, v192, v139
	v_fma_f32 v140, -v145, v193, v140
	v_fma_f32 v2, v2, v194, v137
	v_fma_f32 v13, v13, v195, v138
	v_fma_f32 v12, v12, v196, v139
	v_fma_f32 v8, v8, v197, v140
	s_waitcnt lgkmcnt(6)
	v_mul_f32 v137, v228, v220
	v_mul_f32 v138, v228, v221
	v_mul_f32 v145, v2, v208
	v_fma_f32 v145, v13, v209, v145
	v_fma_f32 v145, v12, v210, v145
	v_fma_f32 v145, v8, v211, v145
	ds_read_b128 v[164:167], v10 offset:43008
	ds_read_b128 v[168:171], v10 offset:43264
	ds_read_b128 v[172:175], v10 offset:43520
	ds_read_b128 v[176:179], v10 offset:43776
	ds_read_b128 v[180:183], v10 offset:44032
	ds_read_b32 v184, v11 offset:43008
	v_add_f32_dpp v145, v145, v145 quad_perm:[1,0,3,2] row_mask:0xf bank_mask:0xf bound_ctrl:1
	v_mul_f32 v157, v2, v202
	v_fma_f32 v157, v13, v203, v157
	v_add_f32_dpp v145, v145, v145 quad_perm:[2,3,0,1] row_mask:0xf bank_mask:0xf bound_ctrl:1
	v_fma_f32 v157, v12, v204, v157
	v_fma_f32 v157, v8, v205, v157
	v_add_f32_dpp v145, v145, v145 row_half_mirror row_mask:0xf bank_mask:0xf bound_ctrl:1
	v_mul_f32 v139, v228, v222
	v_mul_f32 v140, v228, v223
	v_add_f32_dpp v145, v145, v145 row_mirror row_mask:0xf bank_mask:0xf bound_ctrl:1
	v_fma_f32 v137, -v145, v212, v137
	v_fma_f32 v138, -v145, v213, v138
	v_fma_f32 v139, -v145, v214, v139
	v_fma_f32 v140, -v145, v215, v140
	v_fma_f32 v2, v2, v216, v137
	v_fma_f32 v13, v13, v217, v138
	v_fma_f32 v12, v12, v218, v139
	v_fma_f32 v8, v8, v219, v140
	s_waitcnt lgkmcnt(6)
	v_mul_f32 v137, v250, v242
	v_mul_f32 v138, v250, v243
	v_mul_f32 v145, v2, v230
	v_fma_f32 v145, v13, v231, v145
	v_fma_f32 v145, v12, v232, v145
	v_fma_f32 v145, v8, v233, v145
	ds_read_b128 v[186:189], v10 offset:44544
	ds_read_b128 v[190:193], v10 offset:44800
	ds_read_b128 v[194:197], v10 offset:45056
	ds_read_b128 v[198:201], v10 offset:45312
	ds_read_b128 v[202:205], v10 offset:45568
	ds_read_b32 v206, v11 offset:44544
	v_add_f32_dpp v145, v145, v145 quad_perm:[1,0,3,2] row_mask:0xf bank_mask:0xf bound_ctrl:1
	v_mul_f32 v158, v2, v224
	v_fma_f32 v158, v13, v225, v158
	v_add_f32_dpp v145, v145, v145 quad_perm:[2,3,0,1] row_mask:0xf bank_mask:0xf bound_ctrl:1
	v_fma_f32 v158, v12, v226, v158
	v_fma_f32 v158, v8, v227, v158
	v_add_f32_dpp v145, v145, v145 row_half_mirror row_mask:0xf bank_mask:0xf bound_ctrl:1
	v_mul_f32 v139, v250, v244
	v_mul_f32 v140, v250, v245
	v_add_f32_dpp v145, v145, v145 row_mirror row_mask:0xf bank_mask:0xf bound_ctrl:1
	v_fma_f32 v137, -v145, v234, v137
	v_fma_f32 v138, -v145, v235, v138
	v_fma_f32 v139, -v145, v236, v139
	v_fma_f32 v140, -v145, v237, v140
	v_fma_f32 v2, v2, v238, v137
	v_fma_f32 v13, v13, v239, v138
	v_fma_f32 v12, v12, v240, v139
	v_fma_f32 v8, v8, v241, v140
	s_waitcnt lgkmcnt(6)
	v_mul_f32 v137, v184, v176
	v_mul_f32 v138, v184, v177
	v_mul_f32 v145, v2, v164
	v_fma_f32 v145, v13, v165, v145
	v_fma_f32 v145, v12, v166, v145
	v_fma_f32 v145, v8, v167, v145
	ds_read_b128 v[208:211], v10 offset:46080
	ds_read_b128 v[212:215], v10 offset:46336
	ds_read_b128 v[216:219], v10 offset:46592
	ds_read_b128 v[220:223], v10 offset:46848
	ds_read_b128 v[224:227], v10 offset:47104
	ds_read_b32 v228, v11 offset:46080
	v_add_f32_dpp v145, v145, v145 quad_perm:[1,0,3,2] row_mask:0xf bank_mask:0xf bound_ctrl:1
	v_mul_f32 v159, v2, v246
	v_fma_f32 v159, v13, v247, v159
	v_add_f32_dpp v145, v145, v145 quad_perm:[2,3,0,1] row_mask:0xf bank_mask:0xf bound_ctrl:1
	v_fma_f32 v159, v12, v248, v159
	v_fma_f32 v159, v8, v249, v159
	v_add_f32_dpp v145, v145, v145 row_half_mirror row_mask:0xf bank_mask:0xf bound_ctrl:1
	v_mul_f32 v139, v184, v178
	v_mul_f32 v140, v184, v179
	v_add_f32_dpp v145, v145, v145 row_mirror row_mask:0xf bank_mask:0xf bound_ctrl:1
	v_fma_f32 v137, -v145, v168, v137
	v_fma_f32 v138, -v145, v169, v138
	v_fma_f32 v139, -v145, v170, v139
	v_fma_f32 v140, -v145, v171, v140
	v_fma_f32 v2, v2, v172, v137
	v_fma_f32 v13, v13, v173, v138
	v_fma_f32 v12, v12, v174, v139
	v_fma_f32 v8, v8, v175, v140
	s_waitcnt lgkmcnt(6)
	v_mul_f32 v137, v206, v198
	v_mul_f32 v138, v206, v199
	v_mul_f32 v145, v2, v186
	v_fma_f32 v145, v13, v187, v145
	v_fma_f32 v145, v12, v188, v145
	v_fma_f32 v145, v8, v189, v145
	ds_read_b128 v[230:233], v10 offset:47616
	ds_read_b128 v[234:237], v10 offset:47872
	ds_read_b128 v[238:241], v10 offset:48128
	ds_read_b128 v[242:245], v10 offset:48384
	ds_read_b128 v[246:249], v10 offset:48640
	ds_read_b32 v250, v11 offset:47616
	v_add_f32_dpp v145, v145, v145 quad_perm:[1,0,3,2] row_mask:0xf bank_mask:0xf bound_ctrl:1
	v_mul_f32 v160, v2, v180
	v_fma_f32 v160, v13, v181, v160
	v_add_f32_dpp v145, v145, v145 quad_perm:[2,3,0,1] row_mask:0xf bank_mask:0xf bound_ctrl:1
	v_fma_f32 v160, v12, v182, v160
	v_fma_f32 v160, v8, v183, v160
	v_add_f32_dpp v145, v145, v145 row_half_mirror row_mask:0xf bank_mask:0xf bound_ctrl:1
	v_mul_f32 v139, v206, v200
	v_mul_f32 v140, v206, v201
	v_add_f32_dpp v145, v145, v145 row_mirror row_mask:0xf bank_mask:0xf bound_ctrl:1
	v_fma_f32 v137, -v145, v190, v137
	v_fma_f32 v138, -v145, v191, v138
	v_fma_f32 v139, -v145, v192, v139
	v_fma_f32 v140, -v145, v193, v140
	v_fma_f32 v2, v2, v194, v137
	v_fma_f32 v13, v13, v195, v138
	v_fma_f32 v12, v12, v196, v139
	v_fma_f32 v8, v8, v197, v140
	s_waitcnt lgkmcnt(6)
	v_mul_f32 v137, v228, v220
	v_mul_f32 v138, v228, v221
	v_mul_f32 v145, v2, v208
	v_fma_f32 v145, v13, v209, v145
	v_fma_f32 v145, v12, v210, v145
	v_fma_f32 v145, v8, v211, v145
	s_nop 1
	v_add_f32_dpp v145, v145, v145 quad_perm:[1,0,3,2] row_mask:0xf bank_mask:0xf bound_ctrl:1
	v_mul_f32 v161, v2, v202
	v_fma_f32 v161, v13, v203, v161
	v_add_f32_dpp v145, v145, v145 quad_perm:[2,3,0,1] row_mask:0xf bank_mask:0xf bound_ctrl:1
	v_fma_f32 v161, v12, v204, v161
	v_fma_f32 v161, v8, v205, v161
	v_add_f32_dpp v145, v145, v145 row_half_mirror row_mask:0xf bank_mask:0xf bound_ctrl:1
	v_mul_f32 v139, v228, v222
	v_mul_f32 v140, v228, v223
	v_add_f32_dpp v145, v145, v145 row_mirror row_mask:0xf bank_mask:0xf bound_ctrl:1
	v_fma_f32 v137, -v145, v212, v137
	v_fma_f32 v138, -v145, v213, v138
	v_fma_f32 v139, -v145, v214, v139
	v_fma_f32 v140, -v145, v215, v140
	v_fma_f32 v2, v2, v216, v137
	v_fma_f32 v13, v13, v217, v138
	v_fma_f32 v12, v12, v218, v139
	v_fma_f32 v8, v8, v219, v140
	s_waitcnt lgkmcnt(0)
	v_mul_f32 v137, v250, v242
	v_mul_f32 v138, v250, v243
	v_mul_f32 v145, v2, v230
	v_fma_f32 v145, v13, v231, v145
	v_fma_f32 v145, v12, v232, v145
	v_fma_f32 v145, v8, v233, v145
	s_nop 1
	v_add_f32_dpp v145, v145, v145 quad_perm:[1,0,3,2] row_mask:0xf bank_mask:0xf bound_ctrl:1
	v_mul_f32 v162, v2, v224
	v_fma_f32 v162, v13, v225, v162
	v_add_f32_dpp v145, v145, v145 quad_perm:[2,3,0,1] row_mask:0xf bank_mask:0xf bound_ctrl:1
	v_fma_f32 v162, v12, v226, v162
	v_fma_f32 v162, v8, v227, v162
	v_add_f32_dpp v145, v145, v145 row_half_mirror row_mask:0xf bank_mask:0xf bound_ctrl:1
	v_mul_f32 v139, v250, v244
	v_mul_f32 v140, v250, v245
	v_add_f32_dpp v145, v145, v145 row_mirror row_mask:0xf bank_mask:0xf bound_ctrl:1
	v_fma_f32 v137, -v145, v234, v137
	v_fma_f32 v138, -v145, v235, v138
	v_fma_f32 v139, -v145, v236, v139
	v_fma_f32 v140, -v145, v237, v140
	v_fma_f32 v2, v2, v238, v137
	v_fma_f32 v13, v13, v239, v138
	v_fma_f32 v12, v12, v240, v139
	v_fma_f32 v8, v8, v241, v140
	v_mul_f32 v163, v2, v246
	v_fma_f32 v163, v13, v247, v163
	v_fma_f32 v163, v12, v248, v163
	v_fma_f32 v163, v8, v249, v163
	s_nop 0
	v_and_b32 v244, 8, v3
	v_cmp_ne_u32 vcc, 0, v244
	v_cndmask_b32 v244, v156, v148, vcc
	v_cndmask_b32 v245, v157, v149, vcc
	v_cndmask_b32 v246, v158, v150, vcc
	v_cndmask_b32 v247, v159, v151, vcc
	v_cndmask_b32 v230, v148, v156, vcc
	v_cndmask_b32 v231, v149, v157, vcc
	v_cndmask_b32 v232, v150, v158, vcc
	v_cndmask_b32 v233, v151, v159, vcc
	v_add_f32_dpp v230, v244, v230 row_mirror row_mask:0xf bank_mask:0xf bound_ctrl:1
	v_add_f32_dpp v231, v245, v231 row_mirror row_mask:0xf bank_mask:0xf bound_ctrl:1
	v_add_f32_dpp v232, v246, v232 row_mirror row_mask:0xf bank_mask:0xf bound_ctrl:1
	v_add_f32_dpp v233, v247, v233 row_mirror row_mask:0xf bank_mask:0xf bound_ctrl:1
	v_cndmask_b32 v244, v160, v152, vcc
	v_cndmask_b32 v245, v161, v153, vcc
	v_cndmask_b32 v246, v162, v154, vcc
	v_cndmask_b32 v247, v163, v155, vcc
	v_cndmask_b32 v234, v152, v160, vcc
	v_cndmask_b32 v235, v153, v161, vcc
	v_cndmask_b32 v236, v154, v162, vcc
	v_cndmask_b32 v237, v155, v163, vcc
	v_add_f32_dpp v234, v244, v234 row_mirror row_mask:0xf bank_mask:0xf bound_ctrl:1
	v_add_f32_dpp v235, v245, v235 row_mirror row_mask:0xf bank_mask:0xf bound_ctrl:1
	v_add_f32_dpp v236, v246, v236 row_mirror row_mask:0xf bank_mask:0xf bound_ctrl:1
	v_add_f32_dpp v237, v247, v237 row_mirror row_mask:0xf bank_mask:0xf bound_ctrl:1
	v_and_b32 v244, 4, v3
	v_cmp_ne_u32 vcc, 0, v244
	v_cndmask_b32 v244, v234, v230, vcc
	v_cndmask_b32 v245, v235, v231, vcc
	v_cndmask_b32 v246, v236, v232, vcc
	v_cndmask_b32 v247, v237, v233, vcc
	v_cndmask_b32 v238, v230, v234, vcc
	v_cndmask_b32 v239, v231, v235, vcc
	v_cndmask_b32 v240, v232, v236, vcc
	v_cndmask_b32 v241, v233, v237, vcc
	v_add_f32_dpp v238, v244, v238 row_half_mirror row_mask:0xf bank_mask:0xf bound_ctrl:1
	v_add_f32_dpp v239, v245, v239 row_half_mirror row_mask:0xf bank_mask:0xf bound_ctrl:1
	v_add_f32_dpp v240, v246, v240 row_half_mirror row_mask:0xf bank_mask:0xf bound_ctrl:1
	v_add_f32_dpp v241, v247, v241 row_half_mirror row_mask:0xf bank_mask:0xf bound_ctrl:1
	v_and_b32 v244, 2, v3
	v_cmp_ne_u32 vcc, 0, v244
	v_cndmask_b32 v244, v240, v238, vcc
	v_cndmask_b32 v245, v241, v239, vcc
	v_cndmask_b32 v242, v238, v240, vcc
	v_cndmask_b32 v243, v239, v241, vcc
	v_add_f32_dpp v242, v244, v242 quad_perm:[2,3,0,1] row_mask:0xf bank_mask:0xf bound_ctrl:1
	v_add_f32_dpp v243, v245, v243 quad_perm:[2,3,0,1] row_mask:0xf bank_mask:0xf bound_ctrl:1
	v_and_b32 v244, 1, v3
	v_cmp_ne_u32 vcc, 0, v244
	v_cndmask_b32 v244, v243, v242, vcc
	v_cndmask_b32 v245, v242, v243, vcc
	s_nop 0
	v_add_f32_dpp v19, v244, v245 quad_perm:[1,0,3,2] row_mask:0xf bank_mask:0xf bound_ctrl:1

; #define SCAN_BAR() asm volatile("s_barrier" ::: "memory")
; __device__ __forceinline__ void scan_unit(const Ctx& C0, const float* scn, int T, int quarter, const float* S0, float* Sout, unsigned char* obase, int mode) {
;     ...
;         for (int k = 0; k < nch; ++k) {
;             const unsigned aq = (unsigned)(size_t)(C.lds + (k & 1) * SLOT_B) + 16u * (unsigned)q, av = (unsigned)(size_t)(C.lds + (k & 1) * SLOT_B) + (320u + (unsigned)irow) * 4u;
;             float osel0, osel1;
;             asm volatile(SCAN_CHUNK_ASM : "+v"(S0x), "+v"(S1x), "+v"(S2x), "+v"(S3x), "=&v"(osel0), "=&v"(osel1) : "v"(aq), "v"(av), "v"(q) : SCAN_CHUNK_CLOBBERS, "memory");
;             if (mode == 0) { *(float*)(obase + (size_t)(k * 32 + q) * UPITCH_B + rl * 4) = osel0; *(float*)(obase + (size_t)(k * 32 + 16 + q) * UPITCH_B + rl * 4) = osel1; }
;             SCAN_BAR();
;         }
;         if (mode == 0) *(f32x4*)(Sout + irow * 64 + 4 * q) = (f32x4){S0x, S1x, S2x, S3x};
	s_addc_u32 s1, s1, 0
	v_add_co_u32_e32 v16, vcc, s8, v14
	s_cmp_lg_u32 s0, 0x5600000
	s_nop 0
	v_addc_co_u32_e32 v17, vcc, 0, v15, vcc
	v_add_co_u32_e32 v14, vcc, 0xfcaa000, v14
	global_store_dword v[16:17], v18, off offset:768
	s_nop 0
	v_addc_co_u32_e32 v15, vcc, 0, v15, vcc
	global_store_dword v[14:15], v19, off offset:768
	s_barrier
	s_cbranch_scc1 .LBB0_685
	v_readlane_b32 s0, v255, 46
	s_add_i32 s0, s3, s0
	s_ashr_i32 s1, s0, 31
	s_lshl_b64 s[0:1], s[0:1], 17
	v_readlane_b32 s3, v253, 26
	s_add_u32 s0, s3, s0
	v_readlane_b32 s3, v253, 27
	s_addc_u32 s1, s3, s1
	s_lshl_b32 s2, s2, 14
	s_add_u32 s0, s0, s2
	s_addc_u32 s1, s1, 0
	v_lshlrev_b32_e32 v0, 8, v0
	v_lshl_add_u64 v[6:7], s[0:1], 0, v[0:1]
	v_mov_b32_e32 v5, v1
	v_lshl_add_u64 v[6:7], v[6:7], 0, v[4:5]
	v_mov_b32_e32 v3, v13
	v_mov_b32_e32 v4, v12
	v_mov_b32_e32 v5, v8
	global_store_dwordx4 v[6:7], v[2:5], off
